# down/branch/out K-loops: in the 6-DMA load segment issue the LDS-DMAs before the 8 fragment reads (DMA gets the longer lead, reads overlap its issue)
# baseline (speedup 1.0000x reference)
; #define PG8_STAGE(bufoff, gbase, voff) do { _Pragma("unroll") for (int _i = 0; _i < 2; ++_i) \
;         __builtin_amdgcn_global_load_lds((const unsigned*)((const char*)(gbase) + (voff)[_i]), (PG8_LAS unsigned*)(lds + (bufoff) + ldsw + _i * 8192), 16, 0, 0); } while (0)
; #define PG8_LDA(dst, b, h) do { _Pragma("unroll") for (int m = 0; m < 4; ++m) _Pragma("unroll") for (int k = 0; k < 2; ++k) dst[m][k] = *(const PG8_LAS bf16x8*)(lds + PG8_SA(b, h) + aoff + m * 2048 + k * 1024); } while (0)
; #define PG8_LDB(dst, b, h) do { _Pragma("unroll") for (int n = 0; n < 2; ++n) _Pragma("unroll") for (int k = 0; k < 2; ++k) dst[n][k] = *(const PG8_LAS bf16x8*)(lds + PG8_SB(b, h) + boff + n * 2048 + k * 1024); } while (0)
; #define PG8_MMA(ai, bj, At, Bt) do { __builtin_amdgcn_s_setprio(1); _Pragma("unroll") for (int m = 0; m < 4; ++m) _Pragma("unroll") for (int n = 0; n < 2; ++n) _Pragma("unroll") for (int k = 0; k < 2; ++k) \
;         acc[ai][bj][m][n] = __builtin_amdgcn_mfma_f32_16x16x32_bf16(Bt[n][k], At[m][k], acc[ai][bj][m][n], 0, 0, 0); __builtin_amdgcn_s_setprio(0); } while (0)
; #define PG8_WAIT_V(n) asm volatile("s_waitcnt vmcnt(" #n ")" ::: "memory")
; #define PG8_WAIT_L(n) asm volatile("s_waitcnt lgkmcnt(" #n ")" ::: "memory")
; #define PG8_BAR __builtin_amdgcn_s_barrier()
; #define PG8_SCHED __builtin_amdgcn_sched_barrier(0)
; template <class Epi, class Sched, bool ALIGN_EPI = false, bool SP2 = false>
; __device__ __forceinline__ void gemm_phase(PG8_LAS unsigned char* lds, const Gemm g, const Sched& S, const Epi& E) {
;     ...
;         for (int t = 0; t < nt; t += 2) {
;             const bool last = (t == nt - 2);
;             const char* a1 = cA + (size_t)(t + 1) * kstep;
;             const char* a2 = last ? nA : cA + (size_t)(t + 2) * kstep; const char* b2 = last ? nB : cB + (size_t)(t + 2) * kstep;
;             const char* a3 = a2 + kstep; const char* b3 = b2 + kstep;
;             if (last && has_next) S.a_ready(nxt);
;             if constexpr (SP2) {
;             PG8_LDB(B0, 0, 0); PG8_LDB(B1, 0, 1); PG8_SCHED; PG8_LDA(At, 0, 0); PG8_STAGE(PG8_SA(1, 1), a1 + hstep, voffA);
;             PG8_WAIT_V(8); PG8_WAIT_L(0); PG8_BAR; PG8_MMA(0, 0, At, B0); PG8_MMA(0, 1, At, B1); PG8_BAR; PG8_SCHED;
;             if (full) PG8_LDA(At, 0, 1); PG8_STAGE(PG8_SB(0, 0), b2, voffB); PG8_STAGE(PG8_SB(0, 1), b2 + hstep, voffB); PG8_STAGE(PG8_SA(0, 0), a2, voffA);
.LBB0_382:
	s_add_u32 s30, s24, s28
	s_addc_u32 s31, s25, s29
	s_add_u32 s30, s30, 0x100
	s_addc_u32 s31, s31, 0
	s_add_u32 s65, s62, s28
	s_addc_u32 s68, s63, s29
	s_add_i32 s69, 0, 0x10000
	s_cmpk_eq_i32 s28, 0x1500
	s_cselect_b32 s35, s27, s31
	s_cselect_b32 s34, s26, s30
	v_add_u32_e32 v146, s69, v140
	s_cselect_b32 s31, s9, s68
	s_cselect_b32 s30, s8, s65
	s_add_i32 s65, 0, 0x14000
	ds_read_b128 v[142:145], v146
	ds_read_b128 v[154:157], v146 offset:1024
	ds_read_b128 v[158:161], v146 offset:2048
	ds_read_b128 v[162:165], v146 offset:3072
	v_add_u32_e32 v146, s65, v140
	ds_read_b128 v[166:169], v146
	ds_read_b128 v[170:173], v146 offset:1024
	ds_read_b128 v[174:177], v146 offset:2048
	ds_read_b128 v[178:181], v146 offset:3072
	v_lshl_add_u64 v[146:147], v[136:137], 0, s[28:29]
	s_add_i32 m0, s44, 0xc000
	ds_read_b128 v[182:185], v141
	ds_read_b128 v[186:189], v141 offset:1024
	ds_read_b128 v[190:193], v141 offset:2048
	ds_read_b128 v[194:197], v141 offset:3072
	ds_read_b128 v[198:201], v141 offset:4096
	ds_read_b128 v[202:205], v141 offset:5120
	ds_read_b128 v[206:209], v141 offset:6144
	ds_read_b128 v[220:223], v141 offset:7168
	global_load_lds_dwordx4 v[146:147], off
	v_lshl_add_u64 v[146:147], v[138:139], 0, s[28:29]
	s_add_i32 m0, s44, 0xe000
	s_nop 0
	global_load_lds_dwordx4 v[146:147], off
	s_waitcnt vmcnt(8)
	s_waitcnt lgkmcnt(0)
	s_setprio 1
	s_barrier
	v_mfma_f32_16x16x32_bf16 v[114:117], v[142:145], v[182:185], v[114:117]
	v_mfma_f32_16x16x32_bf16 v[82:85], v[158:161], v[182:185], v[82:85]
	v_mfma_f32_16x16x32_bf16 v[122:125], v[142:145], v[190:193], v[122:125]
	v_mfma_f32_16x16x32_bf16 v[94:97], v[158:161], v[190:193], v[94:97]
	v_mfma_f32_16x16x32_bf16 v[126:129], v[142:145], v[198:201], v[126:129]
	v_mfma_f32_16x16x32_bf16 v[106:109], v[158:161], v[198:201], v[106:109]
	v_mfma_f32_16x16x32_bf16 v[118:121], v[142:145], v[206:209], v[118:121]
	v_mfma_f32_16x16x32_bf16 v[110:113], v[158:161], v[206:209], v[110:113]
	v_mfma_f32_16x16x32_bf16 v[114:117], v[154:157], v[186:189], v[114:117]
	v_mfma_f32_16x16x32_bf16 v[82:85], v[162:165], v[186:189], v[82:85]
	v_mfma_f32_16x16x32_bf16 v[122:125], v[154:157], v[194:197], v[122:125]
	v_mfma_f32_16x16x32_bf16 v[94:97], v[162:165], v[194:197], v[94:97]
	v_mfma_f32_16x16x32_bf16 v[126:129], v[154:157], v[202:205], v[126:129]
	v_mfma_f32_16x16x32_bf16 v[106:109], v[162:165], v[202:205], v[106:109]
	v_mfma_f32_16x16x32_bf16 v[118:121], v[154:157], v[220:223], v[118:121]
	v_mfma_f32_16x16x32_bf16 v[110:113], v[162:165], v[220:223], v[110:113]
	v_mfma_f32_16x16x32_bf16 v[26:29], v[166:169], v[182:185], v[26:29]
	v_mfma_f32_16x16x32_bf16 v[2:5], v[174:177], v[182:185], v[2:5]
	v_mfma_f32_16x16x32_bf16 v[34:37], v[166:169], v[190:193], v[34:37]
	v_mfma_f32_16x16x32_bf16 v[6:9], v[174:177], v[190:193], v[6:9]
	v_mfma_f32_16x16x32_bf16 v[42:45], v[166:169], v[198:201], v[42:45]
	v_mfma_f32_16x16x32_bf16 v[10:13], v[174:177], v[198:201], v[10:13]
	v_mfma_f32_16x16x32_bf16 v[46:49], v[166:169], v[206:209], v[46:49]
	v_mfma_f32_16x16x32_bf16 v[14:17], v[174:177], v[206:209], v[14:17]
	v_mfma_f32_16x16x32_bf16 v[26:29], v[170:173], v[186:189], v[26:29]
	v_mfma_f32_16x16x32_bf16 v[2:5], v[178:181], v[186:189], v[2:5]
	v_mfma_f32_16x16x32_bf16 v[34:37], v[170:173], v[194:197], v[34:37]
	v_mfma_f32_16x16x32_bf16 v[6:9], v[178:181], v[194:197], v[6:9]
	v_mfma_f32_16x16x32_bf16 v[42:45], v[170:173], v[202:205], v[42:45]
	v_mfma_f32_16x16x32_bf16 v[10:13], v[178:181], v[202:205], v[10:13]
	v_mfma_f32_16x16x32_bf16 v[46:49], v[170:173], v[220:223], v[46:49]
	v_mfma_f32_16x16x32_bf16 v[14:17], v[178:181], v[220:223], v[14:17]
	s_barrier
	s_setprio 0
	s_add_i32 s68, s69, s43
	v_lshl_add_u64 v[146:147], s[30:31], 0, v[0:1]
	s_mov_b32 m0, s68
	global_load_lds_dwordx4 v[146:147], off
	s_add_i32 m0, s68, 0x2000
	s_add_u32 s68, s30, 0xb0000
	v_lshl_add_u64 v[150:151], s[30:31], 0, v[130:131]
	s_addc_u32 s69, s31, 0
	s_add_i32 s65, s65, s43
	global_load_lds_dwordx4 v[150:151], off
	v_lshl_add_u64 v[210:211], s[68:69], 0, v[0:1]
	s_mov_b32 m0, s65
	v_lshl_add_u64 v[212:213], s[34:35], 0, v[130:131]
	global_load_lds_dwordx4 v[210:211], off
	v_lshl_add_u64 v[210:211], s[68:69], 0, v[130:131]
	s_add_i32 m0, s65, 0x2000
	s_nop 0
	global_load_lds_dwordx4 v[210:211], off
	v_lshl_add_u64 v[210:211], s[34:35], 0, v[0:1]
	s_mov_b32 m0, s44
	s_nop 0
	global_load_lds_dwordx4 v[210:211], off
	s_mov_b32 m0, s45
	s_nop 0
	global_load_lds_dwordx4 v[212:213], off
	ds_read_b128 v[182:185], v141 offset:16384
	ds_read_b128 v[186:189], v141 offset:17408
	ds_read_b128 v[190:193], v141 offset:18432
	ds_read_b128 v[194:197], v141 offset:19456
	ds_read_b128 v[198:201], v141 offset:20480
	ds_read_b128 v[202:205], v141 offset:21504
	ds_read_b128 v[206:209], v141 offset:22528
	ds_read_b128 v[220:223], v141 offset:23552
	s_waitcnt vmcnt(8)
	s_waitcnt lgkmcnt(0)
	s_setprio 1
	s_barrier
; #define PG8_STAGE(bufoff, gbase, voff) do { _Pragma("unroll") for (int _i = 0; _i < 2; ++_i) \
;         __builtin_amdgcn_global_load_lds((const unsigned*)((const char*)(gbase) + (voff)[_i]), (PG8_LAS unsigned*)(lds + (bufoff) + ldsw + _i * 8192), 16, 0, 0); } while (0)
; #define PG8_LDA(dst, b, h) do { _Pragma("unroll") for (int m = 0; m < 4; ++m) _Pragma("unroll") for (int k = 0; k < 2; ++k) dst[m][k] = *(const PG8_LAS bf16x8*)(lds + PG8_SA(b, h) + aoff + m * 2048 + k * 1024); } while (0)
; #define PG8_LDB(dst, b, h) do { _Pragma("unroll") for (int n = 0; n < 2; ++n) _Pragma("unroll") for (int k = 0; k < 2; ++k) dst[n][k] = *(const PG8_LAS bf16x8*)(lds + PG8_SB(b, h) + boff + n * 2048 + k * 1024); } while (0)
; #define PG8_MMA(ai, bj, At, Bt) do { __builtin_amdgcn_s_setprio(1); _Pragma("unroll") for (int m = 0; m < 4; ++m) _Pragma("unroll") for (int n = 0; n < 2; ++n) _Pragma("unroll") for (int k = 0; k < 2; ++k) \
;         acc[ai][bj][m][n] = __builtin_amdgcn_mfma_f32_16x16x32_bf16(Bt[n][k], At[m][k], acc[ai][bj][m][n], 0, 0, 0); __builtin_amdgcn_s_setprio(0); } while (0)
; #define PG8_WAIT_V(n) asm volatile("s_waitcnt vmcnt(" #n ")" ::: "memory")
; #define PG8_WAIT_L(n) asm volatile("s_waitcnt lgkmcnt(" #n ")" ::: "memory")
; #define PG8_BAR __builtin_amdgcn_s_barrier()
; #define PG8_SCHED __builtin_amdgcn_sched_barrier(0)
; template <class Epi, class Sched, bool ALIGN_EPI = false, bool SP2 = false>
; __device__ __forceinline__ void gemm_phase(PG8_LAS unsigned char* lds, const Gemm g, const Sched& S, const Epi& E) {
;     ...
;             PG8_WAIT_V(8); PG8_WAIT_L(0); PG8_BAR; if (full) { PG8_MMA(1, 0, At, B0); PG8_MMA(1, 1, At, B1); } PG8_BAR; PG8_SCHED;
;             PG8_LDB(B0, 1, 0); PG8_LDB(B1, 1, 1); PG8_SCHED; PG8_LDA(At, 1, 0); PG8_STAGE(PG8_SA(0, 1), a2 + hstep, voffA);
;             PG8_WAIT_V(8); PG8_WAIT_L(0); PG8_BAR; PG8_MMA(0, 0, At, B0); PG8_MMA(0, 1, At, B1); PG8_BAR; PG8_SCHED;
	v_mfma_f32_16x16x32_bf16 v[102:105], v[142:145], v[182:185], v[102:105]
	v_mfma_f32_16x16x32_bf16 v[98:101], v[158:161], v[182:185], v[98:101]
	v_mfma_f32_16x16x32_bf16 v[90:93], v[142:145], v[190:193], v[90:93]
	v_mfma_f32_16x16x32_bf16 v[86:89], v[158:161], v[190:193], v[86:89]
	v_mfma_f32_16x16x32_bf16 v[78:81], v[142:145], v[198:201], v[78:81]
	v_mfma_f32_16x16x32_bf16 v[74:77], v[158:161], v[198:201], v[74:77]
	v_mfma_f32_16x16x32_bf16 v[70:73], v[142:145], v[206:209], v[70:73]
	v_mfma_f32_16x16x32_bf16 v[66:69], v[158:161], v[206:209], v[66:69]
	v_mfma_f32_16x16x32_bf16 v[102:105], v[154:157], v[186:189], v[102:105]
	v_mfma_f32_16x16x32_bf16 v[98:101], v[162:165], v[186:189], v[98:101]
	v_mfma_f32_16x16x32_bf16 v[90:93], v[154:157], v[194:197], v[90:93]
	v_mfma_f32_16x16x32_bf16 v[86:89], v[162:165], v[194:197], v[86:89]
	v_mfma_f32_16x16x32_bf16 v[78:81], v[154:157], v[202:205], v[78:81]
	v_mfma_f32_16x16x32_bf16 v[74:77], v[162:165], v[202:205], v[74:77]
	v_mfma_f32_16x16x32_bf16 v[70:73], v[154:157], v[220:223], v[70:73]
	v_mfma_f32_16x16x32_bf16 v[66:69], v[162:165], v[220:223], v[66:69]
	v_mfma_f32_16x16x32_bf16 v[54:57], v[166:169], v[182:185], v[54:57]
	v_mfma_f32_16x16x32_bf16 v[18:21], v[174:177], v[182:185], v[18:21]
	v_mfma_f32_16x16x32_bf16 v[58:61], v[166:169], v[190:193], v[58:61]
	v_mfma_f32_16x16x32_bf16 v[30:33], v[174:177], v[190:193], v[30:33]
	v_mfma_f32_16x16x32_bf16 v[62:65], v[166:169], v[198:201], v[62:65]
	v_mfma_f32_16x16x32_bf16 v[38:41], v[174:177], v[198:201], v[38:41]
	v_mfma_f32_16x16x32_bf16 v[50:53], v[166:169], v[206:209], v[50:53]
	v_mfma_f32_16x16x32_bf16 v[22:25], v[174:177], v[206:209], v[22:25]
	v_mfma_f32_16x16x32_bf16 v[54:57], v[170:173], v[186:189], v[54:57]
	v_mfma_f32_16x16x32_bf16 v[18:21], v[178:181], v[186:189], v[18:21]
	v_mfma_f32_16x16x32_bf16 v[58:61], v[170:173], v[194:197], v[58:61]
	v_mfma_f32_16x16x32_bf16 v[30:33], v[178:181], v[194:197], v[30:33]
	v_mfma_f32_16x16x32_bf16 v[62:65], v[170:173], v[202:205], v[62:65]
	v_mfma_f32_16x16x32_bf16 v[38:41], v[178:181], v[202:205], v[38:41]
	v_mfma_f32_16x16x32_bf16 v[50:53], v[170:173], v[220:223], v[50:53]
	v_mfma_f32_16x16x32_bf16 v[22:25], v[178:181], v[220:223], v[22:25]
	s_barrier
	s_setprio 0
	s_add_i32 s65, 0, 0x18000
	v_add_u32_e32 v149, s65, v140
	s_add_i32 s68, 0, 0x1c000
	ds_read_b128 v[142:145], v149
	ds_read_b128 v[154:157], v149 offset:1024
	ds_read_b128 v[158:161], v149 offset:2048
	ds_read_b128 v[162:165], v149 offset:3072
	v_add_u32_e32 v149, s68, v140
	ds_read_b128 v[166:169], v149
	ds_read_b128 v[170:173], v149 offset:1024
	ds_read_b128 v[174:177], v149 offset:2048
	ds_read_b128 v[178:181], v149 offset:3072
	s_add_u32 s34, s34, 0xb0000
	s_addc_u32 s35, s35, 0
	s_mov_b32 m0, s48
	v_lshl_add_u64 v[214:215], s[34:35], 0, v[0:1]
	ds_read_b128 v[182:185], v141 offset:32768
	ds_read_b128 v[186:189], v141 offset:33792
	ds_read_b128 v[190:193], v141 offset:34816
	ds_read_b128 v[194:197], v141 offset:35840
	ds_read_b128 v[198:201], v141 offset:36864
	ds_read_b128 v[202:205], v141 offset:37888
	ds_read_b128 v[206:209], v141 offset:38912
	ds_read_b128 v[220:223], v141 offset:39936
	global_load_lds_dwordx4 v[214:215], off
	v_lshl_add_u64 v[214:215], s[34:35], 0, v[130:131]
	s_mov_b32 m0, s54
	s_nop 0
	global_load_lds_dwordx4 v[214:215], off
	s_waitcnt vmcnt(8)
	s_waitcnt lgkmcnt(0)
	s_setprio 1
	s_barrier
	v_mfma_f32_16x16x32_bf16 v[114:117], v[142:145], v[182:185], v[114:117]
	v_mfma_f32_16x16x32_bf16 v[82:85], v[158:161], v[182:185], v[82:85]
	v_mfma_f32_16x16x32_bf16 v[122:125], v[142:145], v[190:193], v[122:125]
	v_mfma_f32_16x16x32_bf16 v[94:97], v[158:161], v[190:193], v[94:97]
	v_mfma_f32_16x16x32_bf16 v[126:129], v[142:145], v[198:201], v[126:129]
	v_mfma_f32_16x16x32_bf16 v[106:109], v[158:161], v[198:201], v[106:109]
	v_mfma_f32_16x16x32_bf16 v[118:121], v[142:145], v[206:209], v[118:121]
	v_mfma_f32_16x16x32_bf16 v[110:113], v[158:161], v[206:209], v[110:113]
	v_mfma_f32_16x16x32_bf16 v[114:117], v[154:157], v[186:189], v[114:117]
	v_mfma_f32_16x16x32_bf16 v[82:85], v[162:165], v[186:189], v[82:85]
	v_mfma_f32_16x16x32_bf16 v[122:125], v[154:157], v[194:197], v[122:125]
	v_mfma_f32_16x16x32_bf16 v[94:97], v[162:165], v[194:197], v[94:97]
	v_mfma_f32_16x16x32_bf16 v[126:129], v[154:157], v[202:205], v[126:129]
	v_mfma_f32_16x16x32_bf16 v[106:109], v[162:165], v[202:205], v[106:109]
	v_mfma_f32_16x16x32_bf16 v[118:121], v[154:157], v[220:223], v[118:121]
	v_mfma_f32_16x16x32_bf16 v[110:113], v[162:165], v[220:223], v[110:113]
	v_mfma_f32_16x16x32_bf16 v[26:29], v[166:169], v[182:185], v[26:29]
	v_mfma_f32_16x16x32_bf16 v[2:5], v[174:177], v[182:185], v[2:5]
	v_mfma_f32_16x16x32_bf16 v[34:37], v[166:169], v[190:193], v[34:37]
	v_mfma_f32_16x16x32_bf16 v[6:9], v[174:177], v[190:193], v[6:9]
	v_mfma_f32_16x16x32_bf16 v[42:45], v[166:169], v[198:201], v[42:45]
	v_mfma_f32_16x16x32_bf16 v[10:13], v[174:177], v[198:201], v[10:13]
	v_mfma_f32_16x16x32_bf16 v[46:49], v[166:169], v[206:209], v[46:49]
	v_mfma_f32_16x16x32_bf16 v[14:17], v[174:177], v[206:209], v[14:17]
	v_mfma_f32_16x16x32_bf16 v[26:29], v[170:173], v[186:189], v[26:29]
	v_mfma_f32_16x16x32_bf16 v[2:5], v[178:181], v[186:189], v[2:5]
	v_mfma_f32_16x16x32_bf16 v[34:37], v[170:173], v[194:197], v[34:37]
	v_mfma_f32_16x16x32_bf16 v[6:9], v[178:181], v[194:197], v[6:9]
	v_mfma_f32_16x16x32_bf16 v[42:45], v[170:173], v[202:205], v[42:45]
	v_mfma_f32_16x16x32_bf16 v[10:13], v[178:181], v[202:205], v[10:13]
	v_mfma_f32_16x16x32_bf16 v[46:49], v[170:173], v[220:223], v[46:49]
	v_mfma_f32_16x16x32_bf16 v[14:17], v[178:181], v[220:223], v[14:17]
	s_barrier
; #define PG8_STAGE(bufoff, gbase, voff) do { _Pragma("unroll") for (int _i = 0; _i < 2; ++_i) \
;         __builtin_amdgcn_global_load_lds((const unsigned*)((const char*)(gbase) + (voff)[_i]), (PG8_LAS unsigned*)(lds + (bufoff) + ldsw + _i * 8192), 16, 0, 0); } while (0)
; #define PG8_LDA(dst, b, h) do { _Pragma("unroll") for (int m = 0; m < 4; ++m) _Pragma("unroll") for (int k = 0; k < 2; ++k) dst[m][k] = *(const PG8_LAS bf16x8*)(lds + PG8_SA(b, h) + aoff + m * 2048 + k * 1024); } while (0)
; #define PG8_MMA(ai, bj, At, Bt) do { __builtin_amdgcn_s_setprio(1); _Pragma("unroll") for (int m = 0; m < 4; ++m) _Pragma("unroll") for (int n = 0; n < 2; ++n) _Pragma("unroll") for (int k = 0; k < 2; ++k) \
;         acc[ai][bj][m][n] = __builtin_amdgcn_mfma_f32_16x16x32_bf16(Bt[n][k], At[m][k], acc[ai][bj][m][n], 0, 0, 0); __builtin_amdgcn_s_setprio(0); } while (0)
; #define PG8_WAIT_V(n) asm volatile("s_waitcnt vmcnt(" #n ")" ::: "memory")
; #define PG8_WAIT_L(n) asm volatile("s_waitcnt lgkmcnt(" #n ")" ::: "memory")
; #define PG8_BAR __builtin_amdgcn_s_barrier()
; #define PG8_SCHED __builtin_amdgcn_sched_barrier(0)
; template <class Epi, class Sched, bool ALIGN_EPI = false, bool SP2 = false>
; __device__ __forceinline__ void gemm_phase(PG8_LAS unsigned char* lds, const Gemm g, const Sched& S, const Epi& E) {
;     ...
;             if (full) PG8_LDA(At, 1, 1); PG8_STAGE(PG8_SB(1, 0), b3, voffB); PG8_STAGE(PG8_SB(1, 1), b3 + hstep, voffB); PG8_STAGE(PG8_SA(1, 0), a3, voffA);
;             PG8_WAIT_V(8); PG8_WAIT_L(0); PG8_BAR; if (full) { PG8_MMA(1, 0, At, B0); PG8_MMA(1, 1, At, B1); } PG8_BAR; PG8_SCHED;
;     ...
;         if (!has_next) break;
;         if (!Sched::KEEP || (nxt.pn >> 2) == 0) {
; #pragma unroll
;         for (int a = 0; a < 2; ++a)
; #pragma unroll
;             for (int b = 0; b < 2; ++b)
; #pragma unroll
;                 for (int m = 0; m < 4; ++m)
; #pragma unroll
;                     for (int n = 0; n < 2; ++n) acc[a][b][m][n] = (f32x4){0.f, 0.f, 0.f, 0.f};
;         }
;         cur = nxt; cA = nA; cB = nB; ++ui;
	s_setprio 0
	s_add_i32 s34, s65, s43
	v_lshl_add_u64 v[146:147], v[146:147], 0, s[52:53]
	s_mov_b32 m0, s34
	global_load_lds_dwordx4 v[146:147], off
	s_add_i32 m0, s34, 0x2000
	s_add_u32 s30, s30, 0xb0080
	v_lshl_add_u64 v[146:147], v[150:151], 0, s[52:53]
	s_addc_u32 s31, s31, 0
	s_add_i32 s34, s68, s43
	global_load_lds_dwordx4 v[146:147], off
	v_lshl_add_u64 v[146:147], s[30:31], 0, v[0:1]
	s_mov_b32 m0, s34
	s_nop 0
	global_load_lds_dwordx4 v[146:147], off
	v_lshl_add_u64 v[146:147], s[30:31], 0, v[130:131]
	s_add_i32 m0, s34, 0x2000
	s_nop 0
	global_load_lds_dwordx4 v[146:147], off
	v_lshl_add_u64 v[146:147], v[210:211], 0, s[52:53]
	s_mov_b32 m0, s55
	s_nop 0
	global_load_lds_dwordx4 v[146:147], off
	v_lshl_add_u64 v[146:147], v[212:213], 0, s[52:53]
	s_mov_b32 m0, s56
	s_nop 0
	global_load_lds_dwordx4 v[146:147], off
	ds_read_b128 v[182:185], v141 offset:49152
	ds_read_b128 v[186:189], v141 offset:50176
	ds_read_b128 v[190:193], v141 offset:51200
	ds_read_b128 v[194:197], v141 offset:52224
	ds_read_b128 v[198:201], v141 offset:53248
	ds_read_b128 v[202:205], v141 offset:54272
	ds_read_b128 v[206:209], v141 offset:55296
	ds_read_b128 v[220:223], v141 offset:56320
	s_waitcnt vmcnt(8)
	s_waitcnt lgkmcnt(0)
	s_setprio 1
	s_barrier
	v_mfma_f32_16x16x32_bf16 v[102:105], v[142:145], v[182:185], v[102:105]
	v_mfma_f32_16x16x32_bf16 v[98:101], v[158:161], v[182:185], v[98:101]
	v_mfma_f32_16x16x32_bf16 v[90:93], v[142:145], v[190:193], v[90:93]
	v_mfma_f32_16x16x32_bf16 v[86:89], v[158:161], v[190:193], v[86:89]
	v_mfma_f32_16x16x32_bf16 v[78:81], v[142:145], v[198:201], v[78:81]
	v_mfma_f32_16x16x32_bf16 v[74:77], v[158:161], v[198:201], v[74:77]
	v_mfma_f32_16x16x32_bf16 v[70:73], v[142:145], v[206:209], v[70:73]
	v_mfma_f32_16x16x32_bf16 v[66:69], v[158:161], v[206:209], v[66:69]
	v_mfma_f32_16x16x32_bf16 v[102:105], v[154:157], v[186:189], v[102:105]
	v_mfma_f32_16x16x32_bf16 v[98:101], v[162:165], v[186:189], v[98:101]
	v_mfma_f32_16x16x32_bf16 v[90:93], v[154:157], v[194:197], v[90:93]
	v_mfma_f32_16x16x32_bf16 v[86:89], v[162:165], v[194:197], v[86:89]
	v_mfma_f32_16x16x32_bf16 v[78:81], v[154:157], v[202:205], v[78:81]
	v_mfma_f32_16x16x32_bf16 v[74:77], v[162:165], v[202:205], v[74:77]
	v_mfma_f32_16x16x32_bf16 v[70:73], v[154:157], v[220:223], v[70:73]
	v_mfma_f32_16x16x32_bf16 v[66:69], v[162:165], v[220:223], v[66:69]
	v_mfma_f32_16x16x32_bf16 v[54:57], v[166:169], v[182:185], v[54:57]
	v_mfma_f32_16x16x32_bf16 v[18:21], v[174:177], v[182:185], v[18:21]
	v_mfma_f32_16x16x32_bf16 v[58:61], v[166:169], v[190:193], v[58:61]
	v_mfma_f32_16x16x32_bf16 v[30:33], v[174:177], v[190:193], v[30:33]
	v_mfma_f32_16x16x32_bf16 v[62:65], v[166:169], v[198:201], v[62:65]
	v_mfma_f32_16x16x32_bf16 v[38:41], v[174:177], v[198:201], v[38:41]
	v_mfma_f32_16x16x32_bf16 v[50:53], v[166:169], v[206:209], v[50:53]
	v_mfma_f32_16x16x32_bf16 v[22:25], v[174:177], v[206:209], v[22:25]
	v_mfma_f32_16x16x32_bf16 v[54:57], v[170:173], v[186:189], v[54:57]
	v_mfma_f32_16x16x32_bf16 v[18:21], v[178:181], v[186:189], v[18:21]
	v_mfma_f32_16x16x32_bf16 v[58:61], v[170:173], v[194:197], v[58:61]
	v_mfma_f32_16x16x32_bf16 v[30:33], v[178:181], v[194:197], v[30:33]
	v_mfma_f32_16x16x32_bf16 v[62:65], v[170:173], v[202:205], v[62:65]
	v_mfma_f32_16x16x32_bf16 v[38:41], v[178:181], v[202:205], v[38:41]
	v_mfma_f32_16x16x32_bf16 v[50:53], v[170:173], v[220:223], v[50:53]
	v_mfma_f32_16x16x32_bf16 v[22:25], v[178:181], v[220:223], v[22:25]
	s_barrier
	s_setprio 0
	s_add_i32 s64, s64, 2
	s_add_u32 s28, s28, 0x100
	s_addc_u32 s29, s29, 0
	s_cmp_gt_u32 s64, 41
	s_cbranch_scc0 .LBB0_382
	s_add_u32 s28, s62, 0xffffff00
	s_addc_u32 s29, s63, -1
	s_and_b64 vcc, exec, s[6:7]
	s_cbranch_vccnz .LBB0_369
	v_mov_b32_e32 v22, 0
	s_mov_b32 s18, s59
	s_mov_b32 s37, s60
	s_mov_b64 s[24:25], s[26:27]
	s_mov_b32 s58, s61
	v_mov_b32_e32 v23, v22
	v_mov_b32_e32 v24, v22
	v_mov_b32_e32 v25, v22
	v_mov_b32_e32 v50, v22
	v_mov_b32_e32 v51, v22
	v_mov_b32_e32 v52, v22
	v_mov_b32_e32 v53, v22
	v_mov_b32_e32 v38, v22
	v_mov_b32_e32 v39, v22
	v_mov_b32_e32 v40, v22
	v_mov_b32_e32 v41, v22
	v_mov_b32_e32 v62, v22
	v_mov_b32_e32 v63, v22
	v_mov_b32_e32 v64, v22
	v_mov_b32_e32 v65, v22
	v_mov_b32_e32 v30, v22
	v_mov_b32_e32 v31, v22
	v_mov_b32_e32 v32, v22
	v_mov_b32_e32 v33, v22
	v_mov_b32_e32 v58, v22
	v_mov_b32_e32 v59, v22
	v_mov_b32_e32 v60, v22
	v_mov_b32_e32 v61, v22
	v_mov_b32_e32 v18, v22
	v_mov_b32_e32 v19, v22
	v_mov_b32_e32 v20, v22
	v_mov_b32_e32 v21, v22
	v_mov_b32_e32 v54, v22
	v_mov_b32_e32 v55, v22
	v_mov_b32_e32 v56, v22
	v_mov_b32_e32 v57, v22
	v_mov_b32_e32 v66, v22
	v_mov_b32_e32 v67, v22
	v_mov_b32_e32 v68, v22
	v_mov_b32_e32 v69, v22
	v_mov_b32_e32 v70, v22
	v_mov_b32_e32 v71, v22
	v_mov_b32_e32 v72, v22
	v_mov_b32_e32 v73, v22
	v_mov_b32_e32 v74, v22
	v_mov_b32_e32 v75, v22
	v_mov_b32_e32 v76, v22
	v_mov_b32_e32 v77, v22
	v_mov_b32_e32 v78, v22
	v_mov_b32_e32 v79, v22
	v_mov_b32_e32 v80, v22
	v_mov_b32_e32 v81, v22
	v_mov_b32_e32 v86, v22
	v_mov_b32_e32 v87, v22
	v_mov_b32_e32 v88, v22
	v_mov_b32_e32 v89, v22
	v_mov_b32_e32 v90, v22
	v_mov_b32_e32 v91, v22
	v_mov_b32_e32 v92, v22
	v_mov_b32_e32 v93, v22
	v_mov_b32_e32 v98, v22
	v_mov_b32_e32 v99, v22
	v_mov_b32_e32 v100, v22
	v_mov_b32_e32 v101, v22
	v_mov_b32_e32 v102, v22
	v_mov_b32_e32 v103, v22
	v_mov_b32_e32 v104, v22
	v_mov_b32_e32 v105, v22
	v_mov_b32_e32 v14, v22
	v_mov_b32_e32 v15, v22
	v_mov_b32_e32 v16, v22
	v_mov_b32_e32 v17, v22
	v_mov_b32_e32 v46, v22
	v_mov_b32_e32 v47, v22
	v_mov_b32_e32 v48, v22
	v_mov_b32_e32 v49, v22
	v_mov_b32_e32 v10, v22
	v_mov_b32_e32 v11, v22
	v_mov_b32_e32 v12, v22
	v_mov_b32_e32 v13, v22
	v_mov_b32_e32 v42, v22
	v_mov_b32_e32 v43, v22
	v_mov_b32_e32 v44, v22
	v_mov_b32_e32 v45, v22
	v_mov_b32_e32 v6, v22
	v_mov_b32_e32 v7, v22
	v_mov_b32_e32 v8, v22
	v_mov_b32_e32 v9, v22
	v_mov_b32_e32 v34, v22
	v_mov_b32_e32 v35, v22
	v_mov_b32_e32 v36, v22
	v_mov_b32_e32 v37, v22
	v_mov_b32_e32 v2, v22
	v_mov_b32_e32 v3, v22
	v_mov_b32_e32 v4, v22
	v_mov_b32_e32 v5, v22
	v_mov_b32_e32 v26, v22
	v_mov_b32_e32 v27, v22
	v_mov_b32_e32 v28, v22
	v_mov_b32_e32 v29, v22
	v_mov_b32_e32 v110, v22
	v_mov_b32_e32 v111, v22
	v_mov_b32_e32 v112, v22
	v_mov_b32_e32 v113, v22
	v_mov_b32_e32 v118, v22
	v_mov_b32_e32 v119, v22
	v_mov_b32_e32 v120, v22
	v_mov_b32_e32 v121, v22
	v_mov_b32_e32 v106, v22
	v_mov_b32_e32 v107, v22
	v_mov_b32_e32 v108, v22
	v_mov_b32_e32 v109, v22
	v_mov_b32_e32 v126, v22
	v_mov_b32_e32 v127, v22
	v_mov_b32_e32 v128, v22
	v_mov_b32_e32 v129, v22
	v_mov_b32_e32 v94, v22
	v_mov_b32_e32 v95, v22
	v_mov_b32_e32 v96, v22
	v_mov_b32_e32 v97, v22
	v_mov_b32_e32 v122, v22
	v_mov_b32_e32 v123, v22
	v_mov_b32_e32 v124, v22
	v_mov_b32_e32 v125, v22
	v_mov_b32_e32 v82, v22
	v_mov_b32_e32 v83, v22
	v_mov_b32_e32 v84, v22
	v_mov_b32_e32 v85, v22
	v_mov_b32_e32 v114, v22
	v_mov_b32_e32 v115, v22
	v_mov_b32_e32 v116, v22
	v_mov_b32_e32 v117, v22
	s_andn2_b64 vcc, exec, s[4:5]
	s_cbranch_vccnz .LBB0_370

; #define PG8_STAGE(bufoff, gbase, voff) do { _Pragma("unroll") for (int _i = 0; _i < 2; ++_i) \
;         __builtin_amdgcn_global_load_lds((const unsigned*)((const char*)(gbase) + (voff)[_i]), (PG8_LAS unsigned*)(lds + (bufoff) + ldsw + _i * 8192), 16, 0, 0); } while (0)
; #define PG8_LDA(dst, b, h) do { _Pragma("unroll") for (int m = 0; m < 4; ++m) _Pragma("unroll") for (int k = 0; k < 2; ++k) dst[m][k] = *(const PG8_LAS bf16x8*)(lds + PG8_SA(b, h) + aoff + m * 2048 + k * 1024); } while (0)
; #define PG8_LDB(dst, b, h) do { _Pragma("unroll") for (int n = 0; n < 2; ++n) _Pragma("unroll") for (int k = 0; k < 2; ++k) dst[n][k] = *(const PG8_LAS bf16x8*)(lds + PG8_SB(b, h) + boff + n * 2048 + k * 1024); } while (0)
; #define PG8_MMA(ai, bj, At, Bt) do { __builtin_amdgcn_s_setprio(1); _Pragma("unroll") for (int m = 0; m < 4; ++m) _Pragma("unroll") for (int n = 0; n < 2; ++n) _Pragma("unroll") for (int k = 0; k < 2; ++k) \
;         acc[ai][bj][m][n] = __builtin_amdgcn_mfma_f32_16x16x32_bf16(Bt[n][k], At[m][k], acc[ai][bj][m][n], 0, 0, 0); __builtin_amdgcn_s_setprio(0); } while (0)
; #define PG8_WAIT_V(n) asm volatile("s_waitcnt vmcnt(" #n ")" ::: "memory")
; #define PG8_WAIT_L(n) asm volatile("s_waitcnt lgkmcnt(" #n ")" ::: "memory")
; #define PG8_BAR __builtin_amdgcn_s_barrier()
; #define PG8_SCHED __builtin_amdgcn_sched_barrier(0)
; template <class Epi, class Sched, bool ALIGN_EPI = false, bool SP2 = false>
; __device__ __forceinline__ void gemm_phase(PG8_LAS unsigned char* lds, const Gemm g, const Sched& S, const Epi& E) {
;     ...
;         for (int t = 0; t < nt; t += 2) {
;             const bool last = (t == nt - 2);
;             const char* a1 = cA + (size_t)(t + 1) * kstep;
;             const char* a2 = last ? nA : cA + (size_t)(t + 2) * kstep; const char* b2 = last ? nB : cB + (size_t)(t + 2) * kstep;
;             const char* a3 = a2 + kstep; const char* b3 = b2 + kstep;
;             if (last && has_next) S.a_ready(nxt);
;             if constexpr (SP2) {
;             PG8_LDB(B0, 0, 0); PG8_LDB(B1, 0, 1); PG8_SCHED; PG8_LDA(At, 0, 0); PG8_STAGE(PG8_SA(1, 1), a1 + hstep, voffA);
;             PG8_WAIT_V(8); PG8_WAIT_L(0); PG8_BAR; PG8_MMA(0, 0, At, B0); PG8_MMA(0, 1, At, B1); PG8_BAR; PG8_SCHED;
;             if (full) PG8_LDA(At, 0, 1); PG8_STAGE(PG8_SB(0, 0), b2, voffB); PG8_STAGE(PG8_SB(0, 1), b2 + hstep, voffB); PG8_STAGE(PG8_SA(0, 0), a2, voffA);
.LBB0_1038:
	s_add_u32 s27, s6, 0xfffe0080
	s_addc_u32 s28, s7, -1
	s_add_i32 s54, 0, 0x10000
	s_cmp_eq_u32 s25, 4
	s_cselect_b32 s31, s21, s28
	s_cselect_b32 s30, s20, s27
	v_add_u32_e32 v0, s54, v179
	s_cselect_b32 s29, s0, s19
	s_cselect_b32 s28, s1, s17
	s_add_i32 s27, 0, 0x14000
	ds_read_b128 v[144:147], v0
	ds_read_b128 v[148:151], v0 offset:1024
	ds_read_b128 v[152:155], v0 offset:2048
	ds_read_b128 v[156:159], v0 offset:3072
	v_add_u32_e32 v0, s27, v179
	ds_read_b128 v[160:163], v0
	ds_read_b128 v[164:167], v0 offset:1024
	ds_read_b128 v[168:171], v0 offset:2048
	ds_read_b128 v[172:175], v0 offset:3072
	v_lshl_add_u64 v[2:3], s[6:7], 0, v[140:141]
	s_add_i32 m0, s39, 0xc000
	ds_read_b128 v[182:185], v181
	ds_read_b128 v[186:189], v181 offset:1024
	ds_read_b128 v[190:193], v181 offset:2048
	ds_read_b128 v[194:197], v181 offset:3072
	ds_read_b128 v[198:201], v181 offset:4096
	ds_read_b128 v[202:205], v181 offset:5120
	ds_read_b128 v[206:209], v181 offset:6144
	ds_read_b128 v[220:223], v181 offset:7168
	global_load_lds_dwordx4 v[2:3], off
	v_lshl_add_u64 v[2:3], s[6:7], 0, v[142:143]
	s_add_i32 m0, s39, 0xe000
	s_nop 0
	global_load_lds_dwordx4 v[2:3], off
	s_waitcnt vmcnt(8)
	s_waitcnt lgkmcnt(0)
	s_setprio 1
	s_barrier
	v_mfma_f32_16x16x32_bf16 v[128:131], v[144:147], v[182:185], v[128:131]
	v_mfma_f32_16x16x32_bf16 v[124:127], v[152:155], v[182:185], v[124:127]
	v_mfma_f32_16x16x32_bf16 v[120:123], v[144:147], v[190:193], v[120:123]
	v_mfma_f32_16x16x32_bf16 v[116:119], v[152:155], v[190:193], v[116:119]
	v_mfma_f32_16x16x32_bf16 v[112:115], v[144:147], v[198:201], v[112:115]
	v_mfma_f32_16x16x32_bf16 v[108:111], v[152:155], v[198:201], v[108:111]
	v_mfma_f32_16x16x32_bf16 v[104:107], v[144:147], v[206:209], v[104:107]
	v_mfma_f32_16x16x32_bf16 v[100:103], v[152:155], v[206:209], v[100:103]
	v_mfma_f32_16x16x32_bf16 v[128:131], v[148:151], v[186:189], v[128:131]
	v_mfma_f32_16x16x32_bf16 v[124:127], v[156:159], v[186:189], v[124:127]
	v_mfma_f32_16x16x32_bf16 v[120:123], v[148:151], v[194:197], v[120:123]
	v_mfma_f32_16x16x32_bf16 v[116:119], v[156:159], v[194:197], v[116:119]
	v_mfma_f32_16x16x32_bf16 v[112:115], v[148:151], v[202:205], v[112:115]
	v_mfma_f32_16x16x32_bf16 v[108:111], v[156:159], v[202:205], v[108:111]
	v_mfma_f32_16x16x32_bf16 v[104:107], v[148:151], v[220:223], v[104:107]
	v_mfma_f32_16x16x32_bf16 v[100:103], v[156:159], v[220:223], v[100:103]
	v_mfma_f32_16x16x32_bf16 v[96:99], v[160:163], v[182:185], v[96:99]
	v_mfma_f32_16x16x32_bf16 v[92:95], v[168:171], v[182:185], v[92:95]
	v_mfma_f32_16x16x32_bf16 v[88:91], v[160:163], v[190:193], v[88:91]
	v_mfma_f32_16x16x32_bf16 v[84:87], v[168:171], v[190:193], v[84:87]
	v_mfma_f32_16x16x32_bf16 v[80:83], v[160:163], v[198:201], v[80:83]
	v_mfma_f32_16x16x32_bf16 v[76:79], v[168:171], v[198:201], v[76:79]
	v_mfma_f32_16x16x32_bf16 v[72:75], v[160:163], v[206:209], v[72:75]
	v_mfma_f32_16x16x32_bf16 v[68:71], v[168:171], v[206:209], v[68:71]
	v_mfma_f32_16x16x32_bf16 v[96:99], v[164:167], v[186:189], v[96:99]
	v_mfma_f32_16x16x32_bf16 v[92:95], v[172:175], v[186:189], v[92:95]
	v_mfma_f32_16x16x32_bf16 v[88:91], v[164:167], v[194:197], v[88:91]
	v_mfma_f32_16x16x32_bf16 v[84:87], v[172:175], v[194:197], v[84:87]
	v_mfma_f32_16x16x32_bf16 v[80:83], v[164:167], v[202:205], v[80:83]
	v_mfma_f32_16x16x32_bf16 v[76:79], v[172:175], v[202:205], v[76:79]
	v_mfma_f32_16x16x32_bf16 v[72:75], v[164:167], v[220:223], v[72:75]
	v_mfma_f32_16x16x32_bf16 v[68:71], v[172:175], v[220:223], v[68:71]
	s_barrier
	s_setprio 0
	s_add_i32 s54, s54, s38
	v_lshl_add_u64 v[176:177], s[28:29], 0, v[134:135]
	s_mov_b32 m0, s54
	global_load_lds_dwordx4 v[176:177], off
	s_add_i32 m0, s54, 0x2000
	s_add_u32 s54, s28, 0x20000
	v_lshl_add_u64 v[210:211], s[28:29], 0, v[138:139]
	s_addc_u32 s55, s29, 0
	s_add_i32 s27, s27, s38
	global_load_lds_dwordx4 v[210:211], off
	v_lshl_add_u64 v[2:3], s[54:55], 0, v[134:135]
	s_mov_b32 m0, s27
	v_lshl_add_u64 v[212:213], s[30:31], 0, v[132:133]
	global_load_lds_dwordx4 v[2:3], off
	v_lshl_add_u64 v[2:3], s[54:55], 0, v[138:139]
	s_add_i32 m0, s27, 0x2000
	v_lshl_add_u64 v[214:215], s[30:31], 0, v[136:137]
	global_load_lds_dwordx4 v[2:3], off
	s_mov_b32 m0, s39
	s_nop 0
	global_load_lds_dwordx4 v[212:213], off
	s_mov_b32 m0, s40
	s_nop 0
	global_load_lds_dwordx4 v[214:215], off
	ds_read_b128 v[182:185], v181 offset:16384
	ds_read_b128 v[186:189], v181 offset:17408
	ds_read_b128 v[190:193], v181 offset:18432
	ds_read_b128 v[194:197], v181 offset:19456
	ds_read_b128 v[198:201], v181 offset:20480
	ds_read_b128 v[202:205], v181 offset:21504
	ds_read_b128 v[206:209], v181 offset:22528
	ds_read_b128 v[220:223], v181 offset:23552
	s_waitcnt vmcnt(8)
	s_waitcnt lgkmcnt(0)
	s_setprio 1
	s_barrier
; #define PG8_STAGE(bufoff, gbase, voff) do { _Pragma("unroll") for (int _i = 0; _i < 2; ++_i) \
;         __builtin_amdgcn_global_load_lds((const unsigned*)((const char*)(gbase) + (voff)[_i]), (PG8_LAS unsigned*)(lds + (bufoff) + ldsw + _i * 8192), 16, 0, 0); } while (0)
; #define PG8_LDA(dst, b, h) do { _Pragma("unroll") for (int m = 0; m < 4; ++m) _Pragma("unroll") for (int k = 0; k < 2; ++k) dst[m][k] = *(const PG8_LAS bf16x8*)(lds + PG8_SA(b, h) + aoff + m * 2048 + k * 1024); } while (0)
; #define PG8_LDB(dst, b, h) do { _Pragma("unroll") for (int n = 0; n < 2; ++n) _Pragma("unroll") for (int k = 0; k < 2; ++k) dst[n][k] = *(const PG8_LAS bf16x8*)(lds + PG8_SB(b, h) + boff + n * 2048 + k * 1024); } while (0)
; #define PG8_MMA(ai, bj, At, Bt) do { __builtin_amdgcn_s_setprio(1); _Pragma("unroll") for (int m = 0; m < 4; ++m) _Pragma("unroll") for (int n = 0; n < 2; ++n) _Pragma("unroll") for (int k = 0; k < 2; ++k) \
;         acc[ai][bj][m][n] = __builtin_amdgcn_mfma_f32_16x16x32_bf16(Bt[n][k], At[m][k], acc[ai][bj][m][n], 0, 0, 0); __builtin_amdgcn_s_setprio(0); } while (0)
; #define PG8_WAIT_V(n) asm volatile("s_waitcnt vmcnt(" #n ")" ::: "memory")
; #define PG8_WAIT_L(n) asm volatile("s_waitcnt lgkmcnt(" #n ")" ::: "memory")
; #define PG8_BAR __builtin_amdgcn_s_barrier()
; #define PG8_SCHED __builtin_amdgcn_sched_barrier(0)
; template <class Epi, class Sched, bool ALIGN_EPI = false, bool SP2 = false>
; __device__ __forceinline__ void gemm_phase(PG8_LAS unsigned char* lds, const Gemm g, const Sched& S, const Epi& E) {
;     ...
;             PG8_WAIT_V(8); PG8_WAIT_L(0); PG8_BAR; if (full) { PG8_MMA(1, 0, At, B0); PG8_MMA(1, 1, At, B1); } PG8_BAR; PG8_SCHED;
;             PG8_LDB(B0, 1, 0); PG8_LDB(B1, 1, 1); PG8_SCHED; PG8_LDA(At, 1, 0); PG8_STAGE(PG8_SA(0, 1), a2 + hstep, voffA);
;             PG8_WAIT_V(8); PG8_WAIT_L(0); PG8_BAR; PG8_MMA(0, 0, At, B0); PG8_MMA(0, 1, At, B1); PG8_BAR; PG8_SCHED;
	v_mfma_f32_16x16x32_bf16 v[64:67], v[144:147], v[182:185], v[64:67]
	v_mfma_f32_16x16x32_bf16 v[60:63], v[152:155], v[182:185], v[60:63]
	v_mfma_f32_16x16x32_bf16 v[56:59], v[144:147], v[190:193], v[56:59]
	v_mfma_f32_16x16x32_bf16 v[52:55], v[152:155], v[190:193], v[52:55]
	v_mfma_f32_16x16x32_bf16 v[48:51], v[144:147], v[198:201], v[48:51]
	v_mfma_f32_16x16x32_bf16 v[44:47], v[152:155], v[198:201], v[44:47]
	v_mfma_f32_16x16x32_bf16 v[40:43], v[144:147], v[206:209], v[40:43]
	v_mfma_f32_16x16x32_bf16 v[36:39], v[152:155], v[206:209], v[36:39]
	v_mfma_f32_16x16x32_bf16 v[64:67], v[148:151], v[186:189], v[64:67]
	v_mfma_f32_16x16x32_bf16 v[60:63], v[156:159], v[186:189], v[60:63]
	v_mfma_f32_16x16x32_bf16 v[56:59], v[148:151], v[194:197], v[56:59]
	v_mfma_f32_16x16x32_bf16 v[52:55], v[156:159], v[194:197], v[52:55]
	v_mfma_f32_16x16x32_bf16 v[48:51], v[148:151], v[202:205], v[48:51]
	v_mfma_f32_16x16x32_bf16 v[44:47], v[156:159], v[202:205], v[44:47]
	v_mfma_f32_16x16x32_bf16 v[40:43], v[148:151], v[220:223], v[40:43]
	v_mfma_f32_16x16x32_bf16 v[36:39], v[156:159], v[220:223], v[36:39]
	v_mfma_f32_16x16x32_bf16 v[32:35], v[160:163], v[182:185], v[32:35]
	v_mfma_f32_16x16x32_bf16 v[28:31], v[168:171], v[182:185], v[28:31]
	v_mfma_f32_16x16x32_bf16 v[24:27], v[160:163], v[190:193], v[24:27]
	v_mfma_f32_16x16x32_bf16 v[20:23], v[168:171], v[190:193], v[20:23]
	v_mfma_f32_16x16x32_bf16 v[16:19], v[160:163], v[198:201], v[16:19]
	v_mfma_f32_16x16x32_bf16 v[12:15], v[168:171], v[198:201], v[12:15]
	v_mfma_f32_16x16x32_bf16 v[8:11], v[160:163], v[206:209], v[8:11]
	v_mfma_f32_16x16x32_bf16 v[2:5], v[168:171], v[206:209], v[4:7]
	v_mfma_f32_16x16x32_bf16 v[32:35], v[164:167], v[186:189], v[32:35]
	v_mfma_f32_16x16x32_bf16 v[28:31], v[172:175], v[186:189], v[28:31]
	v_mfma_f32_16x16x32_bf16 v[24:27], v[164:167], v[194:197], v[24:27]
	v_mfma_f32_16x16x32_bf16 v[20:23], v[172:175], v[194:197], v[20:23]
	v_mfma_f32_16x16x32_bf16 v[16:19], v[164:167], v[202:205], v[16:19]
	v_mfma_f32_16x16x32_bf16 v[12:15], v[172:175], v[202:205], v[12:15]
	v_mfma_f32_16x16x32_bf16 v[8:11], v[164:167], v[220:223], v[8:11]
	v_mfma_f32_16x16x32_bf16 v[2:5], v[172:175], v[220:223], v[2:5]
	s_barrier
	s_setprio 0
	s_add_i32 s27, 0, 0x18000
	v_add_u32_e32 v0, s27, v179
	s_add_i32 s54, 0, 0x1c000
	ds_read_b128 v[144:147], v0
	ds_read_b128 v[148:151], v0 offset:1024
	ds_read_b128 v[152:155], v0 offset:2048
	ds_read_b128 v[156:159], v0 offset:3072
	v_add_u32_e32 v0, s54, v179
	ds_read_b128 v[160:163], v0
	ds_read_b128 v[164:167], v0 offset:1024
	ds_read_b128 v[168:171], v0 offset:2048
	ds_read_b128 v[172:175], v0 offset:3072
	s_add_u32 s30, s30, 0x20000
	s_addc_u32 s31, s31, 0
	s_mov_b32 m0, s41
	v_lshl_add_u64 v[6:7], s[30:31], 0, v[132:133]
	ds_read_b128 v[182:185], v181 offset:32768
	ds_read_b128 v[186:189], v181 offset:33792
	ds_read_b128 v[190:193], v181 offset:34816
	ds_read_b128 v[194:197], v181 offset:35840
	ds_read_b128 v[198:201], v181 offset:36864
	ds_read_b128 v[202:205], v181 offset:37888
	ds_read_b128 v[206:209], v181 offset:38912
	ds_read_b128 v[220:223], v181 offset:39936
	global_load_lds_dwordx4 v[6:7], off
	v_lshl_add_u64 v[6:7], s[30:31], 0, v[136:137]
	s_mov_b32 m0, s42
	s_nop 0
	global_load_lds_dwordx4 v[6:7], off
	s_waitcnt vmcnt(8)
	s_waitcnt lgkmcnt(0)
	s_setprio 1
	s_barrier
	v_mfma_f32_16x16x32_bf16 v[128:131], v[144:147], v[182:185], v[128:131]
	v_mfma_f32_16x16x32_bf16 v[124:127], v[152:155], v[182:185], v[124:127]
	v_mfma_f32_16x16x32_bf16 v[120:123], v[144:147], v[190:193], v[120:123]
	v_mfma_f32_16x16x32_bf16 v[116:119], v[152:155], v[190:193], v[116:119]
	v_mfma_f32_16x16x32_bf16 v[112:115], v[144:147], v[198:201], v[112:115]
	v_mfma_f32_16x16x32_bf16 v[108:111], v[152:155], v[198:201], v[108:111]
	v_mfma_f32_16x16x32_bf16 v[104:107], v[144:147], v[206:209], v[104:107]
	v_mfma_f32_16x16x32_bf16 v[100:103], v[152:155], v[206:209], v[100:103]
	v_mfma_f32_16x16x32_bf16 v[128:131], v[148:151], v[186:189], v[128:131]
	v_mfma_f32_16x16x32_bf16 v[124:127], v[156:159], v[186:189], v[124:127]
	v_mfma_f32_16x16x32_bf16 v[120:123], v[148:151], v[194:197], v[120:123]
	v_mfma_f32_16x16x32_bf16 v[116:119], v[156:159], v[194:197], v[116:119]
	v_mfma_f32_16x16x32_bf16 v[112:115], v[148:151], v[202:205], v[112:115]
	v_mfma_f32_16x16x32_bf16 v[108:111], v[156:159], v[202:205], v[108:111]
	v_mfma_f32_16x16x32_bf16 v[104:107], v[148:151], v[220:223], v[104:107]
	v_mfma_f32_16x16x32_bf16 v[100:103], v[156:159], v[220:223], v[100:103]
	v_mfma_f32_16x16x32_bf16 v[96:99], v[160:163], v[182:185], v[96:99]
	v_mfma_f32_16x16x32_bf16 v[92:95], v[168:171], v[182:185], v[92:95]
	v_mfma_f32_16x16x32_bf16 v[88:91], v[160:163], v[190:193], v[88:91]
	v_mfma_f32_16x16x32_bf16 v[84:87], v[168:171], v[190:193], v[84:87]
	v_mfma_f32_16x16x32_bf16 v[80:83], v[160:163], v[198:201], v[80:83]
	v_mfma_f32_16x16x32_bf16 v[76:79], v[168:171], v[198:201], v[76:79]
	v_mfma_f32_16x16x32_bf16 v[72:75], v[160:163], v[206:209], v[72:75]
	v_mfma_f32_16x16x32_bf16 v[68:71], v[168:171], v[206:209], v[68:71]
	v_mfma_f32_16x16x32_bf16 v[96:99], v[164:167], v[186:189], v[96:99]
	v_mfma_f32_16x16x32_bf16 v[92:95], v[172:175], v[186:189], v[92:95]
	v_mfma_f32_16x16x32_bf16 v[88:91], v[164:167], v[194:197], v[88:91]
	v_mfma_f32_16x16x32_bf16 v[84:87], v[172:175], v[194:197], v[84:87]
	v_mfma_f32_16x16x32_bf16 v[80:83], v[164:167], v[202:205], v[80:83]
	v_mfma_f32_16x16x32_bf16 v[76:79], v[172:175], v[202:205], v[76:79]
	v_mfma_f32_16x16x32_bf16 v[72:75], v[164:167], v[220:223], v[72:75]
	v_mfma_f32_16x16x32_bf16 v[68:71], v[172:175], v[220:223], v[68:71]
	s_barrier
; #define PG8_STAGE(bufoff, gbase, voff) do { _Pragma("unroll") for (int _i = 0; _i < 2; ++_i) \
;         __builtin_amdgcn_global_load_lds((const unsigned*)((const char*)(gbase) + (voff)[_i]), (PG8_LAS unsigned*)(lds + (bufoff) + ldsw + _i * 8192), 16, 0, 0); } while (0)
; #define PG8_LDA(dst, b, h) do { _Pragma("unroll") for (int m = 0; m < 4; ++m) _Pragma("unroll") for (int k = 0; k < 2; ++k) dst[m][k] = *(const PG8_LAS bf16x8*)(lds + PG8_SA(b, h) + aoff + m * 2048 + k * 1024); } while (0)
; #define PG8_MMA(ai, bj, At, Bt) do { __builtin_amdgcn_s_setprio(1); _Pragma("unroll") for (int m = 0; m < 4; ++m) _Pragma("unroll") for (int n = 0; n < 2; ++n) _Pragma("unroll") for (int k = 0; k < 2; ++k) \
;         acc[ai][bj][m][n] = __builtin_amdgcn_mfma_f32_16x16x32_bf16(Bt[n][k], At[m][k], acc[ai][bj][m][n], 0, 0, 0); __builtin_amdgcn_s_setprio(0); } while (0)
; #define PG8_WAIT_V(n) asm volatile("s_waitcnt vmcnt(" #n ")" ::: "memory")
; #define PG8_WAIT_L(n) asm volatile("s_waitcnt lgkmcnt(" #n ")" ::: "memory")
; #define PG8_BAR __builtin_amdgcn_s_barrier()
; #define PG8_SCHED __builtin_amdgcn_sched_barrier(0)
; template <class Epi, class Sched, bool ALIGN_EPI = false, bool SP2 = false>
; __device__ __forceinline__ void gemm_phase(PG8_LAS unsigned char* lds, const Gemm g, const Sched& S, const Epi& E) {
;     ...
;             if (full) PG8_LDA(At, 1, 1); PG8_STAGE(PG8_SB(1, 0), b3, voffB); PG8_STAGE(PG8_SB(1, 1), b3 + hstep, voffB); PG8_STAGE(PG8_SA(1, 0), a3, voffA);
;             PG8_WAIT_V(8); PG8_WAIT_L(0); PG8_BAR; if (full) { PG8_MMA(1, 0, At, B0); PG8_MMA(1, 1, At, B1); } PG8_BAR; PG8_SCHED;
;     ...
;         if constexpr (ALIGN_EPI) { if (wr == 0) PG8_BAR; }
;         if constexpr (!Epi::AFTER_DRAIN) { E(acc, cur, wr, wc, fr, fq); S.done(cur); }
;         if (!has_next) break;
	s_setprio 0
	s_add_i32 s27, s27, s38
	v_lshl_add_u64 v[6:7], v[176:177], 0, s[52:53]
	s_mov_b32 m0, s27
	global_load_lds_dwordx4 v[6:7], off
	s_add_i32 m0, s27, 0x2000
	s_add_u32 s28, s28, 0x20080
	v_lshl_add_u64 v[6:7], v[210:211], 0, s[52:53]
	s_addc_u32 s29, s29, 0
	s_add_i32 s27, s54, s38
	global_load_lds_dwordx4 v[6:7], off
	v_lshl_add_u64 v[6:7], s[28:29], 0, v[134:135]
	s_mov_b32 m0, s27
	s_nop 0
	global_load_lds_dwordx4 v[6:7], off
	v_lshl_add_u64 v[6:7], s[28:29], 0, v[138:139]
	s_add_i32 m0, s27, 0x2000
	s_nop 0
	global_load_lds_dwordx4 v[6:7], off
	v_lshl_add_u64 v[6:7], v[212:213], 0, s[52:53]
	s_mov_b32 m0, s43
	s_nop 0
	global_load_lds_dwordx4 v[6:7], off
	v_lshl_add_u64 v[6:7], v[214:215], 0, s[52:53]
	s_mov_b32 m0, s44
	s_nop 0
	global_load_lds_dwordx4 v[6:7], off
	ds_read_b128 v[182:185], v181 offset:49152
	ds_read_b128 v[186:189], v181 offset:50176
	ds_read_b128 v[190:193], v181 offset:51200
	ds_read_b128 v[194:197], v181 offset:52224
	ds_read_b128 v[198:201], v181 offset:53248
	ds_read_b128 v[202:205], v181 offset:54272
	ds_read_b128 v[206:209], v181 offset:55296
	ds_read_b128 v[220:223], v181 offset:56320
	s_waitcnt vmcnt(8)
	s_waitcnt lgkmcnt(0)
	s_setprio 1
	s_barrier
	v_mfma_f32_16x16x32_bf16 v[64:67], v[144:147], v[182:185], v[64:67]
	v_mfma_f32_16x16x32_bf16 v[60:63], v[152:155], v[182:185], v[60:63]
	v_mfma_f32_16x16x32_bf16 v[56:59], v[144:147], v[190:193], v[56:59]
	v_mfma_f32_16x16x32_bf16 v[52:55], v[152:155], v[190:193], v[52:55]
	v_mfma_f32_16x16x32_bf16 v[48:51], v[144:147], v[198:201], v[48:51]
	v_mfma_f32_16x16x32_bf16 v[44:47], v[152:155], v[198:201], v[44:47]
	v_mfma_f32_16x16x32_bf16 v[40:43], v[144:147], v[206:209], v[40:43]
	v_mfma_f32_16x16x32_bf16 v[36:39], v[152:155], v[206:209], v[36:39]
	v_mfma_f32_16x16x32_bf16 v[64:67], v[148:151], v[186:189], v[64:67]
	v_mfma_f32_16x16x32_bf16 v[60:63], v[156:159], v[186:189], v[60:63]
	v_mfma_f32_16x16x32_bf16 v[56:59], v[148:151], v[194:197], v[56:59]
	v_mfma_f32_16x16x32_bf16 v[52:55], v[156:159], v[194:197], v[52:55]
	v_mfma_f32_16x16x32_bf16 v[48:51], v[148:151], v[202:205], v[48:51]
	v_mfma_f32_16x16x32_bf16 v[44:47], v[156:159], v[202:205], v[44:47]
	v_mfma_f32_16x16x32_bf16 v[40:43], v[148:151], v[220:223], v[40:43]
	v_mfma_f32_16x16x32_bf16 v[36:39], v[156:159], v[220:223], v[36:39]
	v_mfma_f32_16x16x32_bf16 v[32:35], v[160:163], v[182:185], v[32:35]
	v_mfma_f32_16x16x32_bf16 v[28:31], v[168:171], v[182:185], v[28:31]
	v_mfma_f32_16x16x32_bf16 v[24:27], v[160:163], v[190:193], v[24:27]
	v_mfma_f32_16x16x32_bf16 v[20:23], v[168:171], v[190:193], v[20:23]
	v_mfma_f32_16x16x32_bf16 v[16:19], v[160:163], v[198:201], v[16:19]
	v_mfma_f32_16x16x32_bf16 v[12:15], v[168:171], v[198:201], v[12:15]
	v_mfma_f32_16x16x32_bf16 v[6:9], v[160:163], v[206:209], v[8:11]
	v_mfma_f32_16x16x32_bf16 v[2:5], v[168:171], v[206:209], v[2:5]
	v_mfma_f32_16x16x32_bf16 v[32:35], v[164:167], v[186:189], v[32:35]
	v_mfma_f32_16x16x32_bf16 v[28:31], v[172:175], v[186:189], v[28:31]
	v_mfma_f32_16x16x32_bf16 v[24:27], v[164:167], v[194:197], v[24:27]
	v_mfma_f32_16x16x32_bf16 v[20:23], v[172:175], v[194:197], v[20:23]
	v_mfma_f32_16x16x32_bf16 v[16:19], v[164:167], v[202:205], v[16:19]
	v_mfma_f32_16x16x32_bf16 v[12:15], v[172:175], v[202:205], v[12:15]
	v_mfma_f32_16x16x32_bf16 v[8:11], v[164:167], v[220:223], v[6:9]
	v_mfma_f32_16x16x32_bf16 v[4:7], v[172:175], v[220:223], v[2:5]
	s_barrier
	s_setprio 0
	s_add_i32 s25, s25, 2
	s_add_u32 s6, s6, 0x100
	s_addc_u32 s7, s7, 0
	s_add_u32 s17, s17, 0x100
	s_addc_u32 s19, s19, 0
	s_cmp_gt_u32 s25, 5
	s_cbranch_scc0 .LBB0_1038
	s_and_b64 vcc, exec, s[14:15]
	s_cbranch_vccz .LBB0_1041
	s_barrier

; #define PG8_STAGE(bufoff, gbase, voff) do { _Pragma("unroll") for (int _i = 0; _i < 2; ++_i) \
;         __builtin_amdgcn_global_load_lds((const unsigned*)((const char*)(gbase) + (voff)[_i]), (PG8_LAS unsigned*)(lds + (bufoff) + ldsw + _i * 8192), 16, 0, 0); } while (0)
; #define PG8_LDA(dst, b, h) do { _Pragma("unroll") for (int m = 0; m < 4; ++m) _Pragma("unroll") for (int k = 0; k < 2; ++k) dst[m][k] = *(const PG8_LAS bf16x8*)(lds + PG8_SA(b, h) + aoff + m * 2048 + k * 1024); } while (0)
; #define PG8_LDB(dst, b, h) do { _Pragma("unroll") for (int n = 0; n < 2; ++n) _Pragma("unroll") for (int k = 0; k < 2; ++k) dst[n][k] = *(const PG8_LAS bf16x8*)(lds + PG8_SB(b, h) + boff + n * 2048 + k * 1024); } while (0)
; #define PG8_MMA(ai, bj, At, Bt) do { __builtin_amdgcn_s_setprio(1); _Pragma("unroll") for (int m = 0; m < 4; ++m) _Pragma("unroll") for (int n = 0; n < 2; ++n) _Pragma("unroll") for (int k = 0; k < 2; ++k) \
;         acc[ai][bj][m][n] = __builtin_amdgcn_mfma_f32_16x16x32_bf16(Bt[n][k], At[m][k], acc[ai][bj][m][n], 0, 0, 0); __builtin_amdgcn_s_setprio(0); } while (0)
; #define PG8_WAIT_V(n) asm volatile("s_waitcnt vmcnt(" #n ")" ::: "memory")
; #define PG8_WAIT_L(n) asm volatile("s_waitcnt lgkmcnt(" #n ")" ::: "memory")
; #define PG8_BAR __builtin_amdgcn_s_barrier()
; #define PG8_SCHED __builtin_amdgcn_sched_barrier(0)
; template <class Epi, class Sched, bool ALIGN_EPI = false, bool SP2 = false>
; __device__ __forceinline__ void gemm_phase(PG8_LAS unsigned char* lds, const Gemm g, const Sched& S, const Epi& E) {
;     ...
;         for (int t = 0; t < nt; t += 2) {
;             const bool last = (t == nt - 2);
;             const char* a1 = cA + (size_t)(t + 1) * kstep;
;             const char* a2 = last ? nA : cA + (size_t)(t + 2) * kstep; const char* b2 = last ? nB : cB + (size_t)(t + 2) * kstep;
;             const char* a3 = a2 + kstep; const char* b3 = b2 + kstep;
;             if (last && has_next) S.a_ready(nxt);
;             if constexpr (SP2) {
;             PG8_LDB(B0, 0, 0); PG8_LDB(B1, 0, 1); PG8_SCHED; PG8_LDA(At, 0, 0); PG8_STAGE(PG8_SA(1, 1), a1 + hstep, voffA);
;             PG8_WAIT_V(8); PG8_WAIT_L(0); PG8_BAR; PG8_MMA(0, 0, At, B0); PG8_MMA(0, 1, At, B1); PG8_BAR; PG8_SCHED;
;             if (full) PG8_LDA(At, 0, 1); PG8_STAGE(PG8_SB(0, 0), b2, voffB); PG8_STAGE(PG8_SB(0, 1), b2 + hstep, voffB); PG8_STAGE(PG8_SA(0, 0), a2, voffA);
.LBB0_1149:
	s_add_u32 s30, s18, s28
	s_addc_u32 s31, s19, s29
	s_add_u32 s30, s30, 0x100
	s_addc_u32 s31, s31, 0
	s_add_u32 s62, s57, s28
	s_addc_u32 s63, s58, s29
	s_add_i32 s64, 0, 0x10000
	s_cmpk_eq_i32 s28, 0x700
	s_cselect_b32 s35, s23, s31
	s_cselect_b32 s34, s59, s30
	v_add_u32_e32 v143, s64, v140
	s_cselect_b32 s31, s21, s63
	s_cselect_b32 s30, s60, s62
	s_add_i32 s65, 0, 0x14000
	ds_read_b128 v[144:147], v143
	ds_read_b128 v[148:151], v143 offset:1024
	ds_read_b128 v[152:155], v143 offset:2048
	ds_read_b128 v[156:159], v143 offset:3072
	v_add_u32_e32 v143, s65, v140
	ds_read_b128 v[160:163], v143
	ds_read_b128 v[164:167], v143 offset:1024
	ds_read_b128 v[168:171], v143 offset:2048
	ds_read_b128 v[174:177], v143 offset:3072
	v_lshl_add_u64 v[210:211], v[136:137], 0, s[28:29]
	s_add_i32 m0, s41, 0xc000
	ds_read_b128 v[178:181], v141
	ds_read_b128 v[182:185], v141 offset:1024
	ds_read_b128 v[186:189], v141 offset:2048
	ds_read_b128 v[190:193], v141 offset:3072
	ds_read_b128 v[194:197], v141 offset:4096
	ds_read_b128 v[198:201], v141 offset:5120
	ds_read_b128 v[202:205], v141 offset:6144
	ds_read_b128 v[206:209], v141 offset:7168
	global_load_lds_dwordx4 v[210:211], off
	v_lshl_add_u64 v[210:211], v[138:139], 0, s[28:29]
	s_add_i32 m0, s41, 0xe000
	s_nop 0
	global_load_lds_dwordx4 v[210:211], off
	s_waitcnt vmcnt(8)
	s_waitcnt lgkmcnt(0)
	s_setprio 1
	s_barrier
	v_mfma_f32_16x16x32_bf16 v[126:129], v[144:147], v[178:181], v[126:129]
	v_mfma_f32_16x16x32_bf16 v[86:89], v[152:155], v[178:181], v[86:89]
	v_mfma_f32_16x16x32_bf16 v[114:117], v[144:147], v[186:189], v[114:117]
	v_mfma_f32_16x16x32_bf16 v[82:85], v[152:155], v[186:189], v[82:85]
	v_mfma_f32_16x16x32_bf16 v[122:125], v[144:147], v[194:197], v[122:125]
	v_mfma_f32_16x16x32_bf16 v[106:109], v[152:155], v[194:197], v[106:109]
	v_mfma_f32_16x16x32_bf16 v[118:121], v[144:147], v[202:205], v[118:121]
	v_mfma_f32_16x16x32_bf16 v[110:113], v[152:155], v[202:205], v[110:113]
	v_mfma_f32_16x16x32_bf16 v[126:129], v[148:151], v[182:185], v[126:129]
	v_mfma_f32_16x16x32_bf16 v[86:89], v[156:159], v[182:185], v[86:89]
	v_mfma_f32_16x16x32_bf16 v[114:117], v[148:151], v[190:193], v[114:117]
	v_mfma_f32_16x16x32_bf16 v[82:85], v[156:159], v[190:193], v[82:85]
	v_mfma_f32_16x16x32_bf16 v[122:125], v[148:151], v[198:201], v[122:125]
	v_mfma_f32_16x16x32_bf16 v[106:109], v[156:159], v[198:201], v[106:109]
	v_mfma_f32_16x16x32_bf16 v[118:121], v[148:151], v[206:209], v[118:121]
	v_mfma_f32_16x16x32_bf16 v[110:113], v[156:159], v[206:209], v[110:113]
	v_mfma_f32_16x16x32_bf16 v[22:25], v[160:163], v[178:181], v[22:25]
	v_mfma_f32_16x16x32_bf16 v[6:9], v[168:171], v[178:181], v[6:9]
	v_mfma_f32_16x16x32_bf16 v[18:21], v[160:163], v[186:189], v[18:21]
	v_mfma_f32_16x16x32_bf16 v[2:5], v[168:171], v[186:189], v[2:5]
	v_mfma_f32_16x16x32_bf16 v[38:41], v[160:163], v[194:197], v[38:41]
	v_mfma_f32_16x16x32_bf16 v[10:13], v[168:171], v[194:197], v[10:13]
	v_mfma_f32_16x16x32_bf16 v[34:37], v[160:163], v[202:205], v[34:37]
	v_mfma_f32_16x16x32_bf16 v[14:17], v[168:171], v[202:205], v[14:17]
	v_mfma_f32_16x16x32_bf16 v[22:25], v[164:167], v[182:185], v[22:25]
	v_mfma_f32_16x16x32_bf16 v[6:9], v[174:177], v[182:185], v[6:9]
	v_mfma_f32_16x16x32_bf16 v[18:21], v[164:167], v[190:193], v[18:21]
	v_mfma_f32_16x16x32_bf16 v[2:5], v[174:177], v[190:193], v[2:5]
	v_mfma_f32_16x16x32_bf16 v[38:41], v[164:167], v[198:201], v[38:41]
	v_mfma_f32_16x16x32_bf16 v[10:13], v[174:177], v[198:201], v[10:13]
	v_mfma_f32_16x16x32_bf16 v[34:37], v[164:167], v[206:209], v[34:37]
	v_mfma_f32_16x16x32_bf16 v[14:17], v[174:177], v[206:209], v[14:17]
	s_barrier
	s_setprio 0
	s_add_i32 s62, s64, s40
	v_lshl_add_u64 v[210:211], s[30:31], 0, v[0:1]
	s_mov_b32 m0, s62
	global_load_lds_dwordx4 v[210:211], off
	s_add_i32 m0, s62, 0x2000
	s_add_u32 s62, s30, 0x40000
	v_lshl_add_u64 v[212:213], s[30:31], 0, v[130:131]
	s_addc_u32 s63, s31, 0
	s_add_i32 s64, s65, s40
	global_load_lds_dwordx4 v[212:213], off
	v_lshl_add_u64 v[214:215], s[62:63], 0, v[0:1]
	s_mov_b32 m0, s64
	v_lshl_add_u64 v[220:221], s[34:35], 0, v[130:131]
	global_load_lds_dwordx4 v[214:215], off
	v_lshl_add_u64 v[214:215], s[62:63], 0, v[130:131]
	s_add_i32 m0, s64, 0x2000
	s_nop 0
	global_load_lds_dwordx4 v[214:215], off
	v_lshl_add_u64 v[214:215], s[34:35], 0, v[0:1]
	s_mov_b32 m0, s41
	s_nop 0
	global_load_lds_dwordx4 v[214:215], off
	s_mov_b32 m0, s42
	s_nop 0
	global_load_lds_dwordx4 v[220:221], off
	ds_read_b128 v[178:181], v141 offset:16384
	ds_read_b128 v[182:185], v141 offset:17408
	ds_read_b128 v[186:189], v141 offset:18432
	ds_read_b128 v[190:193], v141 offset:19456
	ds_read_b128 v[194:197], v141 offset:20480
	ds_read_b128 v[198:201], v141 offset:21504
	ds_read_b128 v[202:205], v141 offset:22528
	ds_read_b128 v[206:209], v141 offset:23552
	s_waitcnt vmcnt(8)
	s_waitcnt lgkmcnt(0)
	s_setprio 1
	s_barrier
; #define PG8_STAGE(bufoff, gbase, voff) do { _Pragma("unroll") for (int _i = 0; _i < 2; ++_i) \
;         __builtin_amdgcn_global_load_lds((const unsigned*)((const char*)(gbase) + (voff)[_i]), (PG8_LAS unsigned*)(lds + (bufoff) + ldsw + _i * 8192), 16, 0, 0); } while (0)
; #define PG8_LDA(dst, b, h) do { _Pragma("unroll") for (int m = 0; m < 4; ++m) _Pragma("unroll") for (int k = 0; k < 2; ++k) dst[m][k] = *(const PG8_LAS bf16x8*)(lds + PG8_SA(b, h) + aoff + m * 2048 + k * 1024); } while (0)
; #define PG8_LDB(dst, b, h) do { _Pragma("unroll") for (int n = 0; n < 2; ++n) _Pragma("unroll") for (int k = 0; k < 2; ++k) dst[n][k] = *(const PG8_LAS bf16x8*)(lds + PG8_SB(b, h) + boff + n * 2048 + k * 1024); } while (0)
; #define PG8_MMA(ai, bj, At, Bt) do { __builtin_amdgcn_s_setprio(1); _Pragma("unroll") for (int m = 0; m < 4; ++m) _Pragma("unroll") for (int n = 0; n < 2; ++n) _Pragma("unroll") for (int k = 0; k < 2; ++k) \
;         acc[ai][bj][m][n] = __builtin_amdgcn_mfma_f32_16x16x32_bf16(Bt[n][k], At[m][k], acc[ai][bj][m][n], 0, 0, 0); __builtin_amdgcn_s_setprio(0); } while (0)
; #define PG8_WAIT_V(n) asm volatile("s_waitcnt vmcnt(" #n ")" ::: "memory")
; #define PG8_WAIT_L(n) asm volatile("s_waitcnt lgkmcnt(" #n ")" ::: "memory")
; #define PG8_BAR __builtin_amdgcn_s_barrier()
; #define PG8_SCHED __builtin_amdgcn_sched_barrier(0)
; template <class Epi, class Sched, bool ALIGN_EPI = false, bool SP2 = false>
; __device__ __forceinline__ void gemm_phase(PG8_LAS unsigned char* lds, const Gemm g, const Sched& S, const Epi& E) {
;     ...
;             PG8_WAIT_V(8); PG8_WAIT_L(0); PG8_BAR; if (full) { PG8_MMA(1, 0, At, B0); PG8_MMA(1, 1, At, B1); } PG8_BAR; PG8_SCHED;
;             PG8_LDB(B0, 1, 0); PG8_LDB(B1, 1, 1); PG8_SCHED; PG8_LDA(At, 1, 0); PG8_STAGE(PG8_SA(0, 1), a2 + hstep, voffA);
;             PG8_WAIT_V(8); PG8_WAIT_L(0); PG8_BAR; PG8_MMA(0, 0, At, B0); PG8_MMA(0, 1, At, B1); PG8_BAR; PG8_SCHED;
	v_mfma_f32_16x16x32_bf16 v[102:105], v[144:147], v[178:181], v[102:105]
	v_mfma_f32_16x16x32_bf16 v[98:101], v[152:155], v[178:181], v[98:101]
	v_mfma_f32_16x16x32_bf16 v[94:97], v[144:147], v[186:189], v[94:97]
	v_mfma_f32_16x16x32_bf16 v[90:93], v[152:155], v[186:189], v[90:93]
	v_mfma_f32_16x16x32_bf16 v[78:81], v[144:147], v[194:197], v[78:81]
	v_mfma_f32_16x16x32_bf16 v[74:77], v[152:155], v[194:197], v[74:77]
	v_mfma_f32_16x16x32_bf16 v[70:73], v[144:147], v[202:205], v[70:73]
	v_mfma_f32_16x16x32_bf16 v[66:69], v[152:155], v[202:205], v[66:69]
	v_mfma_f32_16x16x32_bf16 v[102:105], v[148:151], v[182:185], v[102:105]
	v_mfma_f32_16x16x32_bf16 v[98:101], v[156:159], v[182:185], v[98:101]
	v_mfma_f32_16x16x32_bf16 v[94:97], v[148:151], v[190:193], v[94:97]
	v_mfma_f32_16x16x32_bf16 v[90:93], v[156:159], v[190:193], v[90:93]
	v_mfma_f32_16x16x32_bf16 v[78:81], v[148:151], v[198:201], v[78:81]
	v_mfma_f32_16x16x32_bf16 v[74:77], v[156:159], v[198:201], v[74:77]
	v_mfma_f32_16x16x32_bf16 v[70:73], v[148:151], v[206:209], v[70:73]
	v_mfma_f32_16x16x32_bf16 v[66:69], v[156:159], v[206:209], v[66:69]
	v_mfma_f32_16x16x32_bf16 v[50:53], v[160:163], v[178:181], v[50:53]
	v_mfma_f32_16x16x32_bf16 v[26:29], v[168:171], v[178:181], v[26:29]
	v_mfma_f32_16x16x32_bf16 v[46:49], v[160:163], v[186:189], v[46:49]
	v_mfma_f32_16x16x32_bf16 v[30:33], v[168:171], v[186:189], v[30:33]
	v_mfma_f32_16x16x32_bf16 v[62:65], v[160:163], v[194:197], v[62:65]
	v_mfma_f32_16x16x32_bf16 v[54:57], v[168:171], v[194:197], v[54:57]
	v_mfma_f32_16x16x32_bf16 v[58:61], v[160:163], v[202:205], v[58:61]
	v_mfma_f32_16x16x32_bf16 v[42:45], v[168:171], v[202:205], v[42:45]
	v_mfma_f32_16x16x32_bf16 v[50:53], v[164:167], v[182:185], v[50:53]
	v_mfma_f32_16x16x32_bf16 v[26:29], v[174:177], v[182:185], v[26:29]
	v_mfma_f32_16x16x32_bf16 v[46:49], v[164:167], v[190:193], v[46:49]
	v_mfma_f32_16x16x32_bf16 v[30:33], v[174:177], v[190:193], v[30:33]
	v_mfma_f32_16x16x32_bf16 v[62:65], v[164:167], v[198:201], v[62:65]
	v_mfma_f32_16x16x32_bf16 v[54:57], v[174:177], v[198:201], v[54:57]
	v_mfma_f32_16x16x32_bf16 v[58:61], v[164:167], v[206:209], v[58:61]
	v_mfma_f32_16x16x32_bf16 v[42:45], v[174:177], v[206:209], v[42:45]
	s_barrier
	s_setprio 0
	s_add_i32 s62, 0, 0x18000
	v_add_u32_e32 v143, s62, v140
	s_add_i32 s63, 0, 0x1c000
	ds_read_b128 v[144:147], v143
	ds_read_b128 v[148:151], v143 offset:1024
	ds_read_b128 v[152:155], v143 offset:2048
	ds_read_b128 v[156:159], v143 offset:3072
	v_add_u32_e32 v143, s63, v140
	ds_read_b128 v[160:163], v143
	ds_read_b128 v[164:167], v143 offset:1024
	ds_read_b128 v[168:171], v143 offset:2048
	ds_read_b128 v[174:177], v143 offset:3072
	s_add_u32 s34, s34, 0x40000
	s_addc_u32 s35, s35, 0
	s_mov_b32 m0, s43
	v_lshl_add_u64 v[222:223], s[34:35], 0, v[0:1]
	ds_read_b128 v[178:181], v141 offset:32768
	ds_read_b128 v[182:185], v141 offset:33792
	ds_read_b128 v[186:189], v141 offset:34816
	ds_read_b128 v[190:193], v141 offset:35840
	ds_read_b128 v[194:197], v141 offset:36864
	ds_read_b128 v[198:201], v141 offset:37888
	ds_read_b128 v[202:205], v141 offset:38912
	ds_read_b128 v[206:209], v141 offset:39936
	global_load_lds_dwordx4 v[222:223], off
	v_lshl_add_u64 v[222:223], s[34:35], 0, v[130:131]
	s_mov_b32 m0, s44
	s_nop 0
	global_load_lds_dwordx4 v[222:223], off
	s_waitcnt vmcnt(8)
	s_waitcnt lgkmcnt(0)
	s_setprio 1
	s_barrier
	v_mfma_f32_16x16x32_bf16 v[126:129], v[144:147], v[178:181], v[126:129]
	v_mfma_f32_16x16x32_bf16 v[86:89], v[152:155], v[178:181], v[86:89]
	v_mfma_f32_16x16x32_bf16 v[114:117], v[144:147], v[186:189], v[114:117]
	v_mfma_f32_16x16x32_bf16 v[82:85], v[152:155], v[186:189], v[82:85]
	v_mfma_f32_16x16x32_bf16 v[122:125], v[144:147], v[194:197], v[122:125]
	v_mfma_f32_16x16x32_bf16 v[106:109], v[152:155], v[194:197], v[106:109]
	v_mfma_f32_16x16x32_bf16 v[118:121], v[144:147], v[202:205], v[118:121]
	v_mfma_f32_16x16x32_bf16 v[110:113], v[152:155], v[202:205], v[110:113]
	v_mfma_f32_16x16x32_bf16 v[126:129], v[148:151], v[182:185], v[126:129]
	v_mfma_f32_16x16x32_bf16 v[86:89], v[156:159], v[182:185], v[86:89]
	v_mfma_f32_16x16x32_bf16 v[114:117], v[148:151], v[190:193], v[114:117]
	v_mfma_f32_16x16x32_bf16 v[82:85], v[156:159], v[190:193], v[82:85]
	v_mfma_f32_16x16x32_bf16 v[122:125], v[148:151], v[198:201], v[122:125]
	v_mfma_f32_16x16x32_bf16 v[106:109], v[156:159], v[198:201], v[106:109]
	v_mfma_f32_16x16x32_bf16 v[118:121], v[148:151], v[206:209], v[118:121]
	v_mfma_f32_16x16x32_bf16 v[110:113], v[156:159], v[206:209], v[110:113]
	v_mfma_f32_16x16x32_bf16 v[22:25], v[160:163], v[178:181], v[22:25]
	v_mfma_f32_16x16x32_bf16 v[6:9], v[168:171], v[178:181], v[6:9]
	v_mfma_f32_16x16x32_bf16 v[18:21], v[160:163], v[186:189], v[18:21]
	v_mfma_f32_16x16x32_bf16 v[2:5], v[168:171], v[186:189], v[2:5]
	v_mfma_f32_16x16x32_bf16 v[38:41], v[160:163], v[194:197], v[38:41]
	v_mfma_f32_16x16x32_bf16 v[10:13], v[168:171], v[194:197], v[10:13]
	v_mfma_f32_16x16x32_bf16 v[34:37], v[160:163], v[202:205], v[34:37]
	v_mfma_f32_16x16x32_bf16 v[14:17], v[168:171], v[202:205], v[14:17]
	v_mfma_f32_16x16x32_bf16 v[22:25], v[164:167], v[182:185], v[22:25]
	v_mfma_f32_16x16x32_bf16 v[6:9], v[174:177], v[182:185], v[6:9]
	v_mfma_f32_16x16x32_bf16 v[18:21], v[164:167], v[190:193], v[18:21]
	v_mfma_f32_16x16x32_bf16 v[2:5], v[174:177], v[190:193], v[2:5]
	v_mfma_f32_16x16x32_bf16 v[38:41], v[164:167], v[198:201], v[38:41]
	v_mfma_f32_16x16x32_bf16 v[10:13], v[174:177], v[198:201], v[10:13]
	v_mfma_f32_16x16x32_bf16 v[34:37], v[164:167], v[206:209], v[34:37]
	v_mfma_f32_16x16x32_bf16 v[14:17], v[174:177], v[206:209], v[14:17]
	s_barrier
; #define PG8_STAGE(bufoff, gbase, voff) do { _Pragma("unroll") for (int _i = 0; _i < 2; ++_i) \
;         __builtin_amdgcn_global_load_lds((const unsigned*)((const char*)(gbase) + (voff)[_i]), (PG8_LAS unsigned*)(lds + (bufoff) + ldsw + _i * 8192), 16, 0, 0); } while (0)
; #define PG8_LDA(dst, b, h) do { _Pragma("unroll") for (int m = 0; m < 4; ++m) _Pragma("unroll") for (int k = 0; k < 2; ++k) dst[m][k] = *(const PG8_LAS bf16x8*)(lds + PG8_SA(b, h) + aoff + m * 2048 + k * 1024); } while (0)
; #define PG8_MMA(ai, bj, At, Bt) do { __builtin_amdgcn_s_setprio(1); _Pragma("unroll") for (int m = 0; m < 4; ++m) _Pragma("unroll") for (int n = 0; n < 2; ++n) _Pragma("unroll") for (int k = 0; k < 2; ++k) \
;         acc[ai][bj][m][n] = __builtin_amdgcn_mfma_f32_16x16x32_bf16(Bt[n][k], At[m][k], acc[ai][bj][m][n], 0, 0, 0); __builtin_amdgcn_s_setprio(0); } while (0)
; #define PG8_WAIT_V(n) asm volatile("s_waitcnt vmcnt(" #n ")" ::: "memory")
; #define PG8_WAIT_L(n) asm volatile("s_waitcnt lgkmcnt(" #n ")" ::: "memory")
; #define PG8_BAR __builtin_amdgcn_s_barrier()
; #define PG8_SCHED __builtin_amdgcn_sched_barrier(0)
; template <class Epi, class Sched, bool ALIGN_EPI = false, bool SP2 = false>
; __device__ __forceinline__ void gemm_phase(PG8_LAS unsigned char* lds, const Gemm g, const Sched& S, const Epi& E) {
;     ...
;             if (full) PG8_LDA(At, 1, 1); PG8_STAGE(PG8_SB(1, 0), b3, voffB); PG8_STAGE(PG8_SB(1, 1), b3 + hstep, voffB); PG8_STAGE(PG8_SA(1, 0), a3, voffA);
;             PG8_WAIT_V(8); PG8_WAIT_L(0); PG8_BAR; if (full) { PG8_MMA(1, 0, At, B0); PG8_MMA(1, 1, At, B1); } PG8_BAR; PG8_SCHED;
;     ...
;         if (!has_next) break;
;         if (!Sched::KEEP || (nxt.pn >> 2) == 0) {
; #pragma unroll
;         for (int a = 0; a < 2; ++a)
; #pragma unroll
;             for (int b = 0; b < 2; ++b)
; #pragma unroll
;                 for (int m = 0; m < 4; ++m)
; #pragma unroll
;                     for (int n = 0; n < 2; ++n) acc[a][b][m][n] = (f32x4){0.f, 0.f, 0.f, 0.f};
;         }
;         cur = nxt; cA = nA; cB = nB; ++ui;
	s_setprio 0
	s_add_i32 s34, s62, s40
	v_lshl_add_u64 v[210:211], v[210:211], 0, s[52:53]
	s_mov_b32 m0, s34
	global_load_lds_dwordx4 v[210:211], off
	s_add_i32 m0, s34, 0x2000
	s_add_u32 s30, s30, 0x40080
	v_lshl_add_u64 v[210:211], v[212:213], 0, s[52:53]
	s_addc_u32 s31, s31, 0
	s_add_i32 s34, s63, s40
	global_load_lds_dwordx4 v[210:211], off
	v_lshl_add_u64 v[210:211], s[30:31], 0, v[0:1]
	s_mov_b32 m0, s34
	s_nop 0
	global_load_lds_dwordx4 v[210:211], off
	v_lshl_add_u64 v[210:211], s[30:31], 0, v[130:131]
	s_add_i32 m0, s34, 0x2000
	s_nop 0
	global_load_lds_dwordx4 v[210:211], off
	v_lshl_add_u64 v[210:211], v[214:215], 0, s[52:53]
	s_mov_b32 m0, s48
	s_nop 0
	global_load_lds_dwordx4 v[210:211], off
	v_lshl_add_u64 v[210:211], v[220:221], 0, s[52:53]
	s_mov_b32 m0, s49
	s_nop 0
	global_load_lds_dwordx4 v[210:211], off
	ds_read_b128 v[178:181], v141 offset:49152
	ds_read_b128 v[182:185], v141 offset:50176
	ds_read_b128 v[186:189], v141 offset:51200
	ds_read_b128 v[190:193], v141 offset:52224
	ds_read_b128 v[194:197], v141 offset:53248
	ds_read_b128 v[198:201], v141 offset:54272
	ds_read_b128 v[202:205], v141 offset:55296
	ds_read_b128 v[206:209], v141 offset:56320
	s_waitcnt vmcnt(8)
	s_waitcnt lgkmcnt(0)
	s_setprio 1
	s_barrier
	v_mfma_f32_16x16x32_bf16 v[102:105], v[144:147], v[178:181], v[102:105]
	v_mfma_f32_16x16x32_bf16 v[98:101], v[152:155], v[178:181], v[98:101]
	v_mfma_f32_16x16x32_bf16 v[94:97], v[144:147], v[186:189], v[94:97]
	v_mfma_f32_16x16x32_bf16 v[90:93], v[152:155], v[186:189], v[90:93]
	v_mfma_f32_16x16x32_bf16 v[78:81], v[144:147], v[194:197], v[78:81]
	v_mfma_f32_16x16x32_bf16 v[74:77], v[152:155], v[194:197], v[74:77]
	v_mfma_f32_16x16x32_bf16 v[70:73], v[144:147], v[202:205], v[70:73]
	v_mfma_f32_16x16x32_bf16 v[66:69], v[152:155], v[202:205], v[66:69]
	v_mfma_f32_16x16x32_bf16 v[102:105], v[148:151], v[182:185], v[102:105]
	v_mfma_f32_16x16x32_bf16 v[98:101], v[156:159], v[182:185], v[98:101]
	v_mfma_f32_16x16x32_bf16 v[94:97], v[148:151], v[190:193], v[94:97]
	v_mfma_f32_16x16x32_bf16 v[90:93], v[156:159], v[190:193], v[90:93]
	v_mfma_f32_16x16x32_bf16 v[78:81], v[148:151], v[198:201], v[78:81]
	v_mfma_f32_16x16x32_bf16 v[74:77], v[156:159], v[198:201], v[74:77]
	v_mfma_f32_16x16x32_bf16 v[70:73], v[148:151], v[206:209], v[70:73]
	v_mfma_f32_16x16x32_bf16 v[66:69], v[156:159], v[206:209], v[66:69]
	v_mfma_f32_16x16x32_bf16 v[50:53], v[160:163], v[178:181], v[50:53]
	v_mfma_f32_16x16x32_bf16 v[26:29], v[168:171], v[178:181], v[26:29]
	v_mfma_f32_16x16x32_bf16 v[46:49], v[160:163], v[186:189], v[46:49]
	v_mfma_f32_16x16x32_bf16 v[30:33], v[168:171], v[186:189], v[30:33]
	v_mfma_f32_16x16x32_bf16 v[62:65], v[160:163], v[194:197], v[62:65]
	v_mfma_f32_16x16x32_bf16 v[54:57], v[168:171], v[194:197], v[54:57]
	v_mfma_f32_16x16x32_bf16 v[58:61], v[160:163], v[202:205], v[58:61]
	v_mfma_f32_16x16x32_bf16 v[42:45], v[168:171], v[202:205], v[42:45]
	v_mfma_f32_16x16x32_bf16 v[50:53], v[164:167], v[182:185], v[50:53]
	v_mfma_f32_16x16x32_bf16 v[26:29], v[174:177], v[182:185], v[26:29]
	v_mfma_f32_16x16x32_bf16 v[46:49], v[164:167], v[190:193], v[46:49]
	v_mfma_f32_16x16x32_bf16 v[30:33], v[174:177], v[190:193], v[30:33]
	v_mfma_f32_16x16x32_bf16 v[62:65], v[164:167], v[198:201], v[62:65]
	v_mfma_f32_16x16x32_bf16 v[54:57], v[174:177], v[198:201], v[54:57]
	v_mfma_f32_16x16x32_bf16 v[58:61], v[164:167], v[206:209], v[58:61]
	v_mfma_f32_16x16x32_bf16 v[42:45], v[174:177], v[206:209], v[42:45]
	s_barrier
	s_setprio 0
	s_add_i32 s61, s61, 2
	s_add_u32 s28, s28, 0x100
	s_addc_u32 s29, s29, 0
	s_cmp_gt_u32 s61, 13
	s_cbranch_scc0 .LBB0_1149
	s_add_u32 s28, s57, 0xffffff00
	s_addc_u32 s29, s58, -1
	s_andn2_b64 vcc, exec, s[6:7]
	s_cbranch_vccnz .LBB0_1152
	v_mov_b32_e32 v42, 0
	s_mov_b32 s14, s20
	s_mov_b32 s12, s22
	s_mov_b64 s[18:19], s[26:27]
	s_mov_b32 s55, s56
	v_mov_b32_e32 v43, v42
	v_mov_b32_e32 v44, v42
	v_mov_b32_e32 v45, v42
	v_mov_b32_e32 v58, v42
	v_mov_b32_e32 v59, v42
	v_mov_b32_e32 v60, v42
	v_mov_b32_e32 v61, v42
	v_mov_b32_e32 v54, v42
	v_mov_b32_e32 v55, v42
	v_mov_b32_e32 v56, v42
	v_mov_b32_e32 v57, v42
	v_mov_b32_e32 v62, v42
	v_mov_b32_e32 v63, v42
	v_mov_b32_e32 v64, v42
	v_mov_b32_e32 v65, v42
	v_mov_b32_e32 v30, v42
	v_mov_b32_e32 v31, v42
	v_mov_b32_e32 v32, v42
	v_mov_b32_e32 v33, v42
	v_mov_b32_e32 v46, v42
	v_mov_b32_e32 v47, v42
	v_mov_b32_e32 v48, v42
	v_mov_b32_e32 v49, v42
	v_mov_b32_e32 v26, v42
	v_mov_b32_e32 v27, v42
	v_mov_b32_e32 v28, v42
	v_mov_b32_e32 v29, v42
	v_mov_b32_e32 v50, v42
	v_mov_b32_e32 v51, v42
	v_mov_b32_e32 v52, v42
	v_mov_b32_e32 v53, v42
	v_mov_b32_e32 v66, v42
	v_mov_b32_e32 v67, v42
	v_mov_b32_e32 v68, v42
	v_mov_b32_e32 v69, v42
	v_mov_b32_e32 v70, v42
	v_mov_b32_e32 v71, v42
	v_mov_b32_e32 v72, v42
	v_mov_b32_e32 v73, v42
	v_mov_b32_e32 v74, v42
	v_mov_b32_e32 v75, v42
	v_mov_b32_e32 v76, v42
	v_mov_b32_e32 v77, v42
	v_mov_b32_e32 v78, v42
	v_mov_b32_e32 v79, v42
	v_mov_b32_e32 v80, v42
	v_mov_b32_e32 v81, v42
	v_mov_b32_e32 v90, v42
	v_mov_b32_e32 v91, v42
	v_mov_b32_e32 v92, v42
	v_mov_b32_e32 v93, v42
	v_mov_b32_e32 v94, v42
	v_mov_b32_e32 v95, v42
	v_mov_b32_e32 v96, v42
	v_mov_b32_e32 v97, v42
	v_mov_b32_e32 v98, v42
	v_mov_b32_e32 v99, v42
	v_mov_b32_e32 v100, v42
	v_mov_b32_e32 v101, v42
	v_mov_b32_e32 v102, v42
	v_mov_b32_e32 v103, v42
	v_mov_b32_e32 v104, v42
	v_mov_b32_e32 v105, v42
	v_mov_b32_e32 v14, v42
	v_mov_b32_e32 v15, v42
	v_mov_b32_e32 v16, v42
	v_mov_b32_e32 v17, v42
	v_mov_b32_e32 v34, v42
	v_mov_b32_e32 v35, v42
	v_mov_b32_e32 v36, v42
	v_mov_b32_e32 v37, v42
	v_mov_b32_e32 v10, v42
	v_mov_b32_e32 v11, v42
	v_mov_b32_e32 v12, v42
	v_mov_b32_e32 v13, v42
	v_mov_b32_e32 v38, v42
	v_mov_b32_e32 v39, v42
	v_mov_b32_e32 v40, v42
	v_mov_b32_e32 v41, v42
	v_mov_b32_e32 v2, v42
	v_mov_b32_e32 v3, v42
	v_mov_b32_e32 v4, v42
	v_mov_b32_e32 v5, v42
	v_mov_b32_e32 v18, v42
	v_mov_b32_e32 v19, v42
	v_mov_b32_e32 v20, v42
	v_mov_b32_e32 v21, v42
	v_mov_b32_e32 v6, v42
	v_mov_b32_e32 v7, v42
	v_mov_b32_e32 v8, v42
	v_mov_b32_e32 v9, v42
	v_mov_b32_e32 v22, v42
	v_mov_b32_e32 v23, v42
	v_mov_b32_e32 v24, v42
	v_mov_b32_e32 v25, v42
	v_mov_b32_e32 v110, v42
	v_mov_b32_e32 v111, v42
	v_mov_b32_e32 v112, v42
	v_mov_b32_e32 v113, v42
	v_mov_b32_e32 v118, v42
	v_mov_b32_e32 v119, v42
	v_mov_b32_e32 v120, v42
	v_mov_b32_e32 v121, v42
	v_mov_b32_e32 v106, v42
	v_mov_b32_e32 v107, v42
	v_mov_b32_e32 v108, v42
	v_mov_b32_e32 v109, v42
	v_mov_b32_e32 v122, v42
	v_mov_b32_e32 v123, v42
	v_mov_b32_e32 v124, v42
	v_mov_b32_e32 v125, v42
	v_mov_b32_e32 v82, v42
	v_mov_b32_e32 v83, v42
	v_mov_b32_e32 v84, v42
	v_mov_b32_e32 v85, v42
	v_mov_b32_e32 v114, v42
	v_mov_b32_e32 v115, v42
	v_mov_b32_e32 v116, v42
	v_mov_b32_e32 v117, v42
	v_mov_b32_e32 v86, v42
	v_mov_b32_e32 v87, v42
	v_mov_b32_e32 v88, v42
	v_mov_b32_e32 v89, v42
	v_mov_b32_e32 v126, v42
	v_mov_b32_e32 v127, v42
	v_mov_b32_e32 v128, v42
	v_mov_b32_e32 v129, v42
	s_branch .LBB0_1153
